# GLA scan sections B2/C rewritten (2ch x 8tok mapping, 32-bit LDS pairs), qe@S A-fragment reads issued up front, P0 silu staging loads batched
# speedup vs baseline: 1.0187x; 1.0187x over previous
; __device__ __forceinline__ void p_adaln(const Args& a, unsigned char* lds, const int mk_wid) {
;     ...
;     const float* c = a.in[1]; const float* cctx = a.in[3]; const float* W = a.in[4]; const float* bada = a.in[5];
;     float* MOD = (float*)(a.ws + WS_MOD);
;     for (int i = tid; i < 17 * 1024; i += 512) { const float v = (i < 16 * 1024) ? c[i] : cctx[i - 16 * 1024]; sl[i] = v * __builtin_amdgcn_rcpf(1.f + __expf(-v)); }
.LBB0_8:
	v_cmp_gt_i32_e32 vcc, 1, v7
	v_cmp_lt_i32_e64 s[2:3], 0, v6
	s_lshr_b32 s70, s33, 6
	s_and_b64 s[2:3], vcc, s[2:3]
	s_and_saveexec_b64 s[12:13], s[2:3]
	s_cbranch_execz .LBB0_21
	s_load_dwordx4 s[4:7], s[0:1], 0x18
	s_load_dwordx2 s[14:15], s[0:1], 0x28
	v_mbcnt_lo_u32_b32 v8, -1, 0
	v_mbcnt_hi_u32_b32 v8, -1, v8
	s_movk_i32 s2, 0x4400
	v_add_u32_e32 v14, s72, v8
	v_cmp_gt_i32_e32 vcc, s2, v14
	s_and_saveexec_b64 s[2:3], vcc
	s_cbranch_execz .LBB0_12
	s_load_dwordx2 s[16:17], s[0:1], 0x8
	s_lshl_b32 s9, s70, 8
	s_add_i32 s9, s9, 0
	v_lshl_add_u32 v9, v8, 2, s9
	v_lshlrev_b32_e32 v2, 2, v14
	v_add_u32_e32 v10, 0x8000, v9
	s_waitcnt lgkmcnt(0)
	global_load_dword v16, v2, s[16:17]
	global_load_dword v17, v2, s[16:17] offset:2048
	v_add_u32_e32 v4, 0x1000, v2
	global_load_dword v18, v4, s[16:17]
	global_load_dword v19, v4, s[16:17] offset:2048
	v_add_u32_e32 v5, 0x2000, v2
	global_load_dword v20, v5, s[16:17]
	global_load_dword v21, v5, s[16:17] offset:2048
	v_add_u32_e32 v11, 0x3000, v2
	global_load_dword v22, v11, s[16:17]
	global_load_dword v23, v11, s[16:17] offset:2048
	v_add_u32_e32 v12, 0x4000, v2
	global_load_dword v24, v12, s[16:17]
	global_load_dword v25, v12, s[16:17] offset:2048
	v_add_u32_e32 v13, 0x5000, v2
	global_load_dword v26, v13, s[16:17]
	global_load_dword v27, v13, s[16:17] offset:2048
	v_add_u32_e32 v3, 0x6000, v2
	global_load_dword v28, v3, s[16:17]
	global_load_dword v29, v3, s[16:17] offset:2048
	v_add_u32_e32 v4, 0x7000, v2
	global_load_dword v30, v4, s[16:17]
	global_load_dword v31, v4, s[16:17] offset:2048
	v_add_u32_e32 v5, 0x8000, v2
	global_load_dword v32, v5, s[16:17]
	global_load_dword v33, v5, s[16:17] offset:2048
	v_add_u32_e32 v11, 0x9000, v2
	global_load_dword v34, v11, s[16:17]
	global_load_dword v35, v11, s[16:17] offset:2048
	v_add_u32_e32 v12, 0xa000, v2
	global_load_dword v36, v12, s[16:17]
	global_load_dword v37, v12, s[16:17] offset:2048
	v_add_u32_e32 v13, 0xb000, v2
	global_load_dword v38, v13, s[16:17]
	global_load_dword v39, v13, s[16:17] offset:2048
	v_add_u32_e32 v3, 0xc000, v2
	global_load_dword v40, v3, s[16:17]
	global_load_dword v41, v3, s[16:17] offset:2048
	v_add_u32_e32 v4, 0xd000, v2
	global_load_dword v42, v4, s[16:17]
	global_load_dword v43, v4, s[16:17] offset:2048
	v_add_u32_e32 v5, 0xe000, v2
	global_load_dword v44, v5, s[16:17]
	global_load_dword v45, v5, s[16:17] offset:2048
	v_add_u32_e32 v11, 0xf000, v2
	global_load_dword v46, v11, s[16:17]
	global_load_dword v47, v11, s[16:17] offset:2048
	global_load_dword v48, v2, s[4:5]
	global_load_dword v49, v2, s[4:5] offset:2048
	s_waitcnt vmcnt(26)
	v_mul_f32_e32 v50, 0xbfb8aa3b, v16
	v_mul_f32_e32 v51, 0xbfb8aa3b, v17
	v_mul_f32_e32 v52, 0xbfb8aa3b, v18
	v_mul_f32_e32 v53, 0xbfb8aa3b, v19
	v_mul_f32_e32 v54, 0xbfb8aa3b, v20
	v_mul_f32_e32 v55, 0xbfb8aa3b, v21
	v_mul_f32_e32 v56, 0xbfb8aa3b, v22
	v_mul_f32_e32 v57, 0xbfb8aa3b, v23
	v_exp_f32_e32 v50, v50
	v_exp_f32_e32 v51, v51
	v_exp_f32_e32 v52, v52
	v_exp_f32_e32 v53, v53
	v_exp_f32_e32 v54, v54
	v_exp_f32_e32 v55, v55
	v_exp_f32_e32 v56, v56
	v_exp_f32_e32 v57, v57
	v_add_f32_e32 v50, 1.0, v50
	v_add_f32_e32 v51, 1.0, v51
	v_add_f32_e32 v52, 1.0, v52
	v_add_f32_e32 v53, 1.0, v53
	v_add_f32_e32 v54, 1.0, v54
	v_add_f32_e32 v55, 1.0, v55
	v_add_f32_e32 v56, 1.0, v56
	v_add_f32_e32 v57, 1.0, v57
	v_rcp_f32_e32 v50, v50
	v_rcp_f32_e32 v51, v51
	v_rcp_f32_e32 v52, v52
	v_rcp_f32_e32 v53, v53
	v_rcp_f32_e32 v54, v54
	v_rcp_f32_e32 v55, v55
	v_rcp_f32_e32 v56, v56
	v_rcp_f32_e32 v57, v57
	v_mul_f32_e32 v16, v16, v50
	v_mul_f32_e32 v17, v17, v51
	v_mul_f32_e32 v18, v18, v52
	v_mul_f32_e32 v19, v19, v53
	v_mul_f32_e32 v20, v20, v54
	v_mul_f32_e32 v21, v21, v55
	v_mul_f32_e32 v22, v22, v56
	v_mul_f32_e32 v23, v23, v57
	ds_write_b32 v9, v16
	ds_write_b32 v9, v17 offset:2048
	ds_write_b32 v9, v18 offset:4096
	ds_write_b32 v9, v19 offset:6144
	ds_write_b32 v9, v20 offset:8192
	ds_write_b32 v9, v21 offset:10240
	ds_write_b32 v9, v22 offset:12288
	ds_write_b32 v9, v23 offset:14336
	s_waitcnt vmcnt(18)
; __device__ __forceinline__ void p_adaln(const Args& a, unsigned char* lds, const int mk_wid) {
;     ...
;     for (int i = tid; i < 17 * 1024; i += 512) { const float v = (i < 16 * 1024) ? c[i] : cctx[i - 16 * 1024]; sl[i] = v * __builtin_amdgcn_rcpf(1.f + __expf(-v)); }
	v_mul_f32_e32 v50, 0xbfb8aa3b, v24
	v_mul_f32_e32 v51, 0xbfb8aa3b, v25
	v_mul_f32_e32 v52, 0xbfb8aa3b, v26
	v_mul_f32_e32 v53, 0xbfb8aa3b, v27
	v_mul_f32_e32 v54, 0xbfb8aa3b, v28
	v_mul_f32_e32 v55, 0xbfb8aa3b, v29
	v_mul_f32_e32 v56, 0xbfb8aa3b, v30
	v_mul_f32_e32 v57, 0xbfb8aa3b, v31
	v_exp_f32_e32 v50, v50
	v_exp_f32_e32 v51, v51
	v_exp_f32_e32 v52, v52
	v_exp_f32_e32 v53, v53
	v_exp_f32_e32 v54, v54
	v_exp_f32_e32 v55, v55
	v_exp_f32_e32 v56, v56
	v_exp_f32_e32 v57, v57
	v_add_f32_e32 v50, 1.0, v50
	v_add_f32_e32 v51, 1.0, v51
	v_add_f32_e32 v52, 1.0, v52
	v_add_f32_e32 v53, 1.0, v53
	v_add_f32_e32 v54, 1.0, v54
	v_add_f32_e32 v55, 1.0, v55
	v_add_f32_e32 v56, 1.0, v56
	v_add_f32_e32 v57, 1.0, v57
	v_rcp_f32_e32 v50, v50
	v_rcp_f32_e32 v51, v51
	v_rcp_f32_e32 v52, v52
	v_rcp_f32_e32 v53, v53
	v_rcp_f32_e32 v54, v54
	v_rcp_f32_e32 v55, v55
	v_rcp_f32_e32 v56, v56
	v_rcp_f32_e32 v57, v57
	v_mul_f32_e32 v24, v24, v50
	v_mul_f32_e32 v25, v25, v51
	v_mul_f32_e32 v26, v26, v52
	v_mul_f32_e32 v27, v27, v53
	v_mul_f32_e32 v28, v28, v54
	v_mul_f32_e32 v29, v29, v55
	v_mul_f32_e32 v30, v30, v56
	v_mul_f32_e32 v31, v31, v57
	ds_write_b32 v9, v24 offset:16384
	ds_write_b32 v9, v25 offset:18432
	ds_write_b32 v9, v26 offset:20480
	ds_write_b32 v9, v27 offset:22528
	ds_write_b32 v9, v28 offset:24576
	ds_write_b32 v9, v29 offset:26624
	ds_write_b32 v9, v30 offset:28672
	ds_write_b32 v9, v31 offset:30720
	s_waitcnt vmcnt(10)
	v_mul_f32_e32 v50, 0xbfb8aa3b, v32
	v_mul_f32_e32 v51, 0xbfb8aa3b, v33
	v_mul_f32_e32 v52, 0xbfb8aa3b, v34
	v_mul_f32_e32 v53, 0xbfb8aa3b, v35
	v_mul_f32_e32 v54, 0xbfb8aa3b, v36
	v_mul_f32_e32 v55, 0xbfb8aa3b, v37
	v_mul_f32_e32 v56, 0xbfb8aa3b, v38
	v_mul_f32_e32 v57, 0xbfb8aa3b, v39
	v_exp_f32_e32 v50, v50
	v_exp_f32_e32 v51, v51
	v_exp_f32_e32 v52, v52
	v_exp_f32_e32 v53, v53
	v_exp_f32_e32 v54, v54
	v_exp_f32_e32 v55, v55
	v_exp_f32_e32 v56, v56
	v_exp_f32_e32 v57, v57
	v_add_f32_e32 v50, 1.0, v50
	v_add_f32_e32 v51, 1.0, v51
	v_add_f32_e32 v52, 1.0, v52
	v_add_f32_e32 v53, 1.0, v53
	v_add_f32_e32 v54, 1.0, v54
	v_add_f32_e32 v55, 1.0, v55
	v_add_f32_e32 v56, 1.0, v56
	v_add_f32_e32 v57, 1.0, v57
	v_rcp_f32_e32 v50, v50
	v_rcp_f32_e32 v51, v51
	v_rcp_f32_e32 v52, v52
	v_rcp_f32_e32 v53, v53
	v_rcp_f32_e32 v54, v54
	v_rcp_f32_e32 v55, v55
	v_rcp_f32_e32 v56, v56
	v_rcp_f32_e32 v57, v57
	v_mul_f32_e32 v32, v32, v50
	v_mul_f32_e32 v33, v33, v51
	v_mul_f32_e32 v34, v34, v52
	v_mul_f32_e32 v35, v35, v53
	v_mul_f32_e32 v36, v36, v54
	v_mul_f32_e32 v37, v37, v55
	v_mul_f32_e32 v38, v38, v56
	v_mul_f32_e32 v39, v39, v57
	ds_write_b32 v10, v32
	ds_write_b32 v10, v33 offset:2048
	ds_write_b32 v10, v34 offset:4096
	ds_write_b32 v10, v35 offset:6144
	ds_write_b32 v10, v36 offset:8192
	ds_write_b32 v10, v37 offset:10240
	ds_write_b32 v10, v38 offset:12288
	ds_write_b32 v10, v39 offset:14336
	s_waitcnt vmcnt(2)
	v_mul_f32_e32 v50, 0xbfb8aa3b, v40
	v_mul_f32_e32 v51, 0xbfb8aa3b, v41
	v_mul_f32_e32 v52, 0xbfb8aa3b, v42
	v_mul_f32_e32 v53, 0xbfb8aa3b, v43
	v_mul_f32_e32 v54, 0xbfb8aa3b, v44
	v_mul_f32_e32 v55, 0xbfb8aa3b, v45
	v_mul_f32_e32 v56, 0xbfb8aa3b, v46
	v_mul_f32_e32 v57, 0xbfb8aa3b, v47
	v_exp_f32_e32 v50, v50
	v_exp_f32_e32 v51, v51
	v_exp_f32_e32 v52, v52
	v_exp_f32_e32 v53, v53
	v_exp_f32_e32 v54, v54
	v_exp_f32_e32 v55, v55
	v_exp_f32_e32 v56, v56
	v_exp_f32_e32 v57, v57
	v_add_f32_e32 v50, 1.0, v50
	v_add_f32_e32 v51, 1.0, v51
	v_add_f32_e32 v52, 1.0, v52
	v_add_f32_e32 v53, 1.0, v53
	v_add_f32_e32 v54, 1.0, v54
	v_add_f32_e32 v55, 1.0, v55
	v_add_f32_e32 v56, 1.0, v56
	v_add_f32_e32 v57, 1.0, v57
	v_rcp_f32_e32 v50, v50
	v_rcp_f32_e32 v51, v51
	v_rcp_f32_e32 v52, v52
	v_rcp_f32_e32 v53, v53
	v_rcp_f32_e32 v54, v54
	v_rcp_f32_e32 v55, v55
	v_rcp_f32_e32 v56, v56
	v_rcp_f32_e32 v57, v57
	v_mul_f32_e32 v40, v40, v50
	v_mul_f32_e32 v41, v41, v51
	v_mul_f32_e32 v42, v42, v52
	v_mul_f32_e32 v43, v43, v53
	v_mul_f32_e32 v44, v44, v54
	v_mul_f32_e32 v45, v45, v55
	v_mul_f32_e32 v46, v46, v56
	v_mul_f32_e32 v47, v47, v57
	ds_write_b32 v10, v40 offset:16384
	ds_write_b32 v10, v41 offset:18432
	ds_write_b32 v10, v42 offset:20480
	ds_write_b32 v10, v43 offset:22528
	ds_write_b32 v10, v44 offset:24576
	ds_write_b32 v10, v45 offset:26624
	ds_write_b32 v10, v46 offset:28672
	ds_write_b32 v10, v47 offset:30720
	s_waitcnt vmcnt(0)
	v_mul_f32_e32 v50, 0xbfb8aa3b, v48
	v_mul_f32_e32 v51, 0xbfb8aa3b, v49
	v_exp_f32_e32 v50, v50
	v_exp_f32_e32 v51, v51
	s_nop 1
	v_add_f32_e32 v50, 1.0, v50
	v_add_f32_e32 v51, 1.0, v51
	s_nop 1
	v_rcp_f32_e32 v50, v50
	v_rcp_f32_e32 v51, v51
	s_nop 1
	v_mul_f32_e32 v48, v48, v50
	v_mul_f32_e32 v49, v49, v51
	ds_write_b32 v10, v48 offset:32768
	ds_write_b32 v10, v49 offset:34816

; __device__ __forceinline__ int crow(int r, int hi) { return (r & 3) + 8 * (r >> 2) + 4 * hi; }
; __device__ __forceinline__ int v_st(int k, int c) { const int kk = (k & ~0xC) | ((k & 4) << 1) | ((k & 8) >> 1); return ((kk >> 3) * 4 + (c >> 5)) * 512 + ((kk & 7) * 32 + (c & 31)) * 2; }
; #define OPAQUE_TID(name) int name = MK_TID; asm volatile("" : "+v"(name))
; __device__ __forceinline__ void scan_unit(const int unit, const Args& a, unsigned char* lds, const int mk_wid) {
;     ...
;         { OPAQUE_TID(t_);
; #pragma unroll
;           for (int p = 0; p < 2; ++p) { const int i_ = p * 32 + (t_ >> 4), c_ = (t_ & 15) * 8; *(bf16x8*)(qe + i_ * QP + c_) = qraw[p]; *(bf16x8*)(ke + i_ * QP + c_) = kraw[p]; }
; #pragma unroll
;           for (int p = 0; p < 4; ++p) { const int i_ = p * 16 + (t_ >> 5), c8 = t_ & 31; *(bf16x8*)(lds + L_V + (c8 >> 4) * 16384 + v_st(i_, (c8 & 15) * 8)) = vraw[p]; }
;           if (t_ < 128) *(bf16x8*)(lds + L_LR + (t_ >> 1) * 32 + (t_ & 1) * 16) = lraw; }
;         __syncthreads();
;         { OPAQUE_TID(t_); const int lane = t_ & 63, r32 = lane & 31, hi = lane >> 5; const int tt = wid >> 2, ct = wid & 3;
;           const bf16x8 af = *(const bf16x8*)(lds + L_LR + (tt * 32 + r32) * 32 + hi * 16);
;           const f32x16 z = __builtin_amdgcn_mfma_f32_32x32x16_bf16(af, upf, f32x16{}, 0, 0, 0);
;           float* lw = las + (tt * 32 + 4 * hi) * 128 + ct * 32 + r32;
; #pragma unroll
;           for (int r = 0; r < 16; ++r) { const float zz = z[r] + biasc;
;               lw[crow(r, 0) * 128] = (fminf(zz, 0.f) - __builtin_amdgcn_logf(1.f + __builtin_amdgcn_exp2f(-1.4426950408889634f * fabsf(zz))) * 0.6931471805599453f) * (1.f / 16.f); } }
;         __syncthreads();
.LBB0_418:
	v_mbcnt_lo_u32_b32 v64, -1, 0
	v_mbcnt_hi_u32_b32 v64, -1, v64
	s_nop 0
	v_add_u32_e32 v64, s72, v64
	s_nop 0
	v_lshlrev_b32_e32 v66, 3, v64
	v_lshrrev_b32_e32 v65, 4, v64
	v_and_b32_e32 v67, 0x78, v66
	v_lshlrev_b32_e32 v67, 1, v67
	v_mul_lo_u32 v65, v65, s51
	v_add3_u32 v65, 0, v67, v65
	s_waitcnt vmcnt(5)
	ds_write_b128 v65, v[128:131]
	ds_write_b128 v65, v[100:103] offset:17408
	s_waitcnt vmcnt(4)
	ds_write_b128 v65, v[132:135] offset:8704
	ds_write_b128 v65, v[104:107] offset:26112
	v_ashrrev_i32_e32 v65, 5, v64
	v_lshlrev_b32_e32 v68, 10, v64
	v_lshrrev_b32_e32 v69, 1, v65
	v_and_b32_e32 v70, 3, v65
	v_and_b32_e32 v68, 0x4000, v68
	v_and_or_b32 v69, v69, 4, v70
	v_add_u32_e32 v68, 0, v68
	v_lshlrev_b32_e32 v69, 6, v69
	v_and_b32_e32 v67, 48, v67
	v_add3_u32 v67, v68, v69, v67
	v_and_b32_e32 v68, 0xfffff0, v65
	v_lshlrev_b32_e32 v69, 1, v65
	v_and_or_b32 v68, v69, 8, v68
	v_bfe_u32 v66, v66, 5, 2
	v_lshrrev_b32_e32 v68, 1, v68
	v_or_b32_e32 v68, v68, v66
	v_lshl_add_u32 v68, v68, 9, v67
	s_waitcnt vmcnt(3)
	ds_write_b128 v68, v[112:115] offset:51200
	v_add_u32_e32 v68, 16, v65
	v_and_b32_e32 v69, 0xfffff0, v68
	v_lshlrev_b32_e32 v68, 1, v68
	v_and_or_b32 v68, v68, 8, v69
	v_lshrrev_b32_e32 v68, 1, v68
	v_or_b32_e32 v68, v68, v66
	v_lshl_add_u32 v68, v68, 9, v67
	s_waitcnt vmcnt(2)
	ds_write_b128 v68, v[116:119] offset:51200
	v_add_u32_e32 v68, 32, v65
	v_and_b32_e32 v69, 0xfffff0, v68
	v_lshlrev_b32_e32 v68, 1, v68
	v_and_or_b32 v68, v68, 8, v69
	v_lshrrev_b32_e32 v68, 1, v68
	v_or_b32_e32 v68, v68, v66
	v_lshl_add_u32 v68, v68, 9, v67
	v_add_u32_e32 v65, 48, v65
	s_waitcnt vmcnt(1)
	ds_write_b128 v68, v[120:123] offset:51200
	v_and_b32_e32 v68, 0xfffff0, v65
	v_lshlrev_b32_e32 v65, 1, v65
	v_and_or_b32 v65, v65, 8, v68
	v_lshrrev_b32_e32 v65, 1, v65
	v_or_b32_e32 v65, v65, v66
	v_lshl_add_u32 v65, v65, 9, v67
	v_cmp_gt_i32_e32 vcc, s52, v64
	s_waitcnt vmcnt(0)
	ds_write_b128 v65, v[124:127] offset:51200
	s_and_saveexec_b64 s[26:27], vcc
	v_lshlrev_b32_e32 v64, 4, v64
	v_and_b32_e32 v65, 0xffffffe0, v64
	v_and_b32_e32 v64, 16, v64
	v_add3_u32 v64, s53, v65, v64
	ds_write_b128 v64, v[96:99]
	s_or_b64 exec, exec, s[26:27]
	s_waitcnt lgkmcnt(0)
	s_barrier
	v_mbcnt_lo_u32_b32 v64, -1, 0
	v_mbcnt_hi_u32_b32 v64, -1, v64
	s_nop 0
	v_add_u32_e32 v64, s72, v64
	s_nop 0
	v_and_b32_e32 v68, 31, v64
	v_bfe_u32 v69, v64, 5, 1
	v_lshlrev_b32_e32 v64, 5, v68
	v_lshlrev_b32_e32 v65, 4, v69
	v_add3_u32 v64, s44, v64, v65
	ds_read_b128 v[64:67], v64
	v_lshlrev_b32_e32 v69, 11, v69
	v_lshlrev_b32_e32 v68, 2, v68
	v_add3_u32 v80, s45, v69, v68
	s_waitcnt lgkmcnt(0)
	v_mfma_f32_32x32x16_bf16 v[64:79], v[64:67], v[108:111], 0
	s_nop 11
	v_add_f32_e32 v64, v156, v64
	v_add_f32_e32 v65, v156, v65
	v_mul_f32_e64 v81, |v64|, s54
	v_mul_f32_e64 v82, |v65|, s54
	v_exp_f32_e32 v81, v81
	v_exp_f32_e32 v82, v82
	v_add_f32_e32 v66, v156, v66
	v_min_f32_e32 v64, 0, v64
	v_add_f32_e32 v81, 1.0, v81
	v_add_f32_e32 v82, 1.0, v82
	v_log_f32_e32 v81, v81
	v_log_f32_e32 v82, v82
	v_min_f32_e32 v65, 0, v65
	v_mul_f32_e64 v83, |v66|, s54
	v_fmac_f32_e32 v64, 0xbf317218, v81
	v_fmac_f32_e32 v65, 0xbf317218, v82
	v_add_f32_e32 v67, v156, v67
	v_exp_f32_e32 v83, v83
	v_mul_f32_e32 v64, 0x3d800000, v64
	v_mul_f32_e32 v65, 0x3d800000, v65
	ds_write2st64_b32 v80, v64, v65 offset1:2
	v_mul_f32_e64 v64, |v67|, s54
	v_exp_f32_e32 v64, v64
	v_add_f32_e32 v65, 1.0, v83
	v_log_f32_e32 v65, v65
	v_min_f32_e32 v66, 0, v66
	v_add_f32_e32 v64, 1.0, v64
	v_log_f32_e32 v64, v64
	v_fmac_f32_e32 v66, 0xbf317218, v65
	v_mul_f32_e32 v65, 0x3d800000, v66
	v_min_f32_e32 v66, 0, v67
	v_fmac_f32_e32 v66, 0xbf317218, v64
	v_mul_f32_e32 v64, 0x3d800000, v66
	ds_write2st64_b32 v80, v65, v64 offset0:4 offset1:6
	v_add_f32_e32 v64, v156, v68
	v_mul_f32_e64 v65, |v64|, s54
	v_add_f32_e32 v66, v156, v69
	v_exp_f32_e32 v65, v65
	v_mul_f32_e64 v67, |v66|, s54
	v_exp_f32_e32 v67, v67
	v_min_f32_e32 v64, 0, v64
	v_add_f32_e32 v65, 1.0, v65
	v_log_f32_e32 v65, v65
	v_add_f32_e32 v67, 1.0, v67
	v_log_f32_e32 v67, v67
	v_fmac_f32_e32 v64, 0xbf317218, v65
	v_min_f32_e32 v65, 0, v66
	v_fmac_f32_e32 v65, 0xbf317218, v67
	v_mul_f32_e32 v64, 0x3d800000, v64
	v_mul_f32_e32 v65, 0x3d800000, v65
	ds_write2st64_b32 v80, v64, v65 offset0:16 offset1:18
	v_add_f32_e32 v64, v156, v70
	v_mul_f32_e64 v65, |v64|, s54
	v_add_f32_e32 v66, v156, v71
	v_exp_f32_e32 v65, v65
	v_mul_f32_e64 v67, |v66|, s54
	v_exp_f32_e32 v67, v67
	v_min_f32_e32 v64, 0, v64
	v_add_f32_e32 v65, 1.0, v65
	v_log_f32_e32 v65, v65
	v_add_f32_e32 v67, 1.0, v67
	v_log_f32_e32 v67, v67
	v_fmac_f32_e32 v64, 0xbf317218, v65
	v_min_f32_e32 v65, 0, v66
	v_fmac_f32_e32 v65, 0xbf317218, v67
	v_mul_f32_e32 v64, 0x3d800000, v64
	v_mul_f32_e32 v65, 0x3d800000, v65
	ds_write2st64_b32 v80, v64, v65 offset0:20 offset1:22
	v_add_f32_e32 v64, v156, v72
	v_mul_f32_e64 v65, |v64|, s54
	v_add_f32_e32 v66, v156, v73
	v_exp_f32_e32 v65, v65
	v_mul_f32_e64 v67, |v66|, s54
	v_exp_f32_e32 v67, v67
	v_min_f32_e32 v64, 0, v64
	v_add_f32_e32 v65, 1.0, v65
	v_log_f32_e32 v65, v65
	v_add_f32_e32 v67, 1.0, v67
	v_log_f32_e32 v67, v67
	v_fmac_f32_e32 v64, 0xbf317218, v65
	v_min_f32_e32 v65, 0, v66
	v_fmac_f32_e32 v65, 0xbf317218, v67
	v_mul_f32_e32 v64, 0x3d800000, v64
	v_mul_f32_e32 v65, 0x3d800000, v65
	ds_write2st64_b32 v80, v64, v65 offset0:32 offset1:34
	v_add_f32_e32 v64, v156, v74
	v_mul_f32_e64 v65, |v64|, s54
	v_add_f32_e32 v66, v156, v75
	v_exp_f32_e32 v65, v65
	v_mul_f32_e64 v67, |v66|, s54
	v_exp_f32_e32 v67, v67
	v_min_f32_e32 v64, 0, v64
	v_add_f32_e32 v65, 1.0, v65
	v_log_f32_e32 v65, v65
	v_add_f32_e32 v67, 1.0, v67
	v_log_f32_e32 v67, v67
	v_fmac_f32_e32 v64, 0xbf317218, v65
	v_min_f32_e32 v65, 0, v66
	v_fmac_f32_e32 v65, 0xbf317218, v67
	v_mul_f32_e32 v64, 0x3d800000, v64
	v_mul_f32_e32 v65, 0x3d800000, v65
	ds_write2st64_b32 v80, v64, v65 offset0:36 offset1:38
	v_add_f32_e32 v64, v156, v76
	v_mul_f32_e64 v65, |v64|, s54
	v_add_f32_e32 v66, v156, v77
	v_exp_f32_e32 v65, v65
	v_mul_f32_e64 v67, |v66|, s54
	v_exp_f32_e32 v67, v67
	v_min_f32_e32 v64, 0, v64
	v_add_f32_e32 v65, 1.0, v65
	v_log_f32_e32 v65, v65
	v_add_f32_e32 v67, 1.0, v67
	v_log_f32_e32 v67, v67
	v_fmac_f32_e32 v64, 0xbf317218, v65
	v_min_f32_e32 v65, 0, v66
	v_fmac_f32_e32 v65, 0xbf317218, v67
	v_mul_f32_e32 v64, 0x3d800000, v64
	v_mul_f32_e32 v65, 0x3d800000, v65
	ds_write2st64_b32 v80, v64, v65 offset0:48 offset1:50
	v_add_f32_e32 v64, v156, v78
	v_mul_f32_e64 v65, |v64|, s54
	v_add_f32_e32 v66, v156, v79
	v_exp_f32_e32 v65, v65
	v_mul_f32_e64 v67, |v66|, s54
	v_exp_f32_e32 v67, v67
	v_min_f32_e32 v64, 0, v64
	v_add_f32_e32 v65, 1.0, v65
	v_log_f32_e32 v65, v65
	v_add_f32_e32 v67, 1.0, v67
	v_log_f32_e32 v67, v67
	v_fmac_f32_e32 v64, 0xbf317218, v65
	v_min_f32_e32 v65, 0, v66
	v_fmac_f32_e32 v65, 0xbf317218, v67
	v_mul_f32_e32 v64, 0x3d800000, v64
	v_mul_f32_e32 v65, 0x3d800000, v65
	ds_write2st64_b32 v80, v64, v65 offset0:52 offset1:54
	s_waitcnt lgkmcnt(0)
	s_barrier
; __device__ __forceinline__ int v_st(int k, int c) { const int kk = (k & ~0xC) | ((k & 4) << 1) | ((k & 8) >> 1); return ((kk >> 3) * 4 + (c >> 5)) * 512 + ((kk & 7) * 32 + (c & 31)) * 2; }
; __device__ __forceinline__ float bf2f(short s) { return __uint_as_float(((unsigned)(unsigned short)s) << 16); }
; __device__ __forceinline__ float bf2f(u16 u) { return __uint_as_float((unsigned)u << 16); }
; #define OPAQUE_TID(name) int name = MK_TID; asm volatile("" : "+v"(name))
; __device__ __forceinline__ void scan_unit(const int unit, const Args& a, unsigned char* lds, const int mk_wid) {
;     ...
;         { OPAQUE_TID(t_); const int c = t_ & 127, g = t_ >> 7;
;           float bl[16]; float run = 0.f;
;           { const float* lp = las + (g * 16) * 128 + c;
; #pragma unroll
;             for (int ii = 0; ii < 16; ++ii) { run += lp[ii * 128]; bl[ii] = run; } }
;           gs[g * 128 + c] = run;
;           __syncthreads();
;           const float g0 = gs[c], g1 = gs[128 + c], g2 = gs[256 + c], g3 = gs[384 + c];
;           const float off = (g > 0 ? g0 : 0.f) + (g > 1 ? g1 : 0.f) + (g > 2 ? g2 : 0.f);
;           const float btot = (g0 + g1) + (g2 + g3);
;           const float dlc = __builtin_amdgcn_exp2f(btot * 1.4426950408889634f);
;           if (g == 0) dl[c] = dlc;
;           u16* qcol = qe + (g * 16) * QP + c; u16* kcol = ke + (g * 16) * QP + c; unsigned char* kdb = lds + L_KD + v_st(g * 16, c);
; #pragma unroll
;           for (int ii = 0; ii < 16; ++ii) { const float bb = bl[ii] + off;
;               const float qf = bf2f(qcol[ii * QP]), kf = bf2f(kcol[ii * QP]);
;               const float e = __builtin_amdgcn_exp2f(bb * 1.4426950408889634f), ker = kf * __builtin_amdgcn_rcpf(e);
	v_mbcnt_lo_u32_b32 v64, -1, 0
	v_mbcnt_hi_u32_b32 v64, -1, v64
	s_lshl_b32 s96, s70, 12
	s_add_i32 s96, s96, s9
	v_lshl_add_u32 v65, v64, 3, s96
	ds_read_b64 v[170:171], v65
	ds_read_b64 v[172:173], v65 offset:512
	ds_read_b64 v[174:175], v65 offset:1024
	ds_read_b64 v[176:177], v65 offset:1536
	ds_read_b64 v[178:179], v65 offset:2048
	ds_read_b64 v[180:181], v65 offset:2560
	ds_read_b64 v[182:183], v65 offset:3072
	ds_read_b64 v[184:185], v65 offset:3584
	s_cmp_gt_u32 s70, 0
	s_cselect_b32 s97, 1.0, 0
	v_mov_b32_e32 v238, s97
	s_cmp_gt_u32 s70, 1
	s_cselect_b32 s97, 1.0, 0
	v_mov_b32_e32 v239, s97
	s_cmp_gt_u32 s70, 2
	s_cselect_b32 s97, 1.0, 0
	v_mov_b32_e32 v240, s97
	s_cmp_gt_u32 s70, 3
	s_cselect_b32 s97, 1.0, 0
	v_mov_b32_e32 v241, s97
	s_cmp_gt_u32 s70, 4
	s_cselect_b32 s97, 1.0, 0
	v_mov_b32_e32 v242, s97
	s_cmp_gt_u32 s70, 5
	s_cselect_b32 s97, 1.0, 0
	v_mov_b32_e32 v243, s97
	s_cmp_gt_u32 s70, 6
	s_cselect_b32 s97, 1.0, 0
	v_mov_b32_e32 v244, s97
	s_lshl_b32 s98, s70, 9
	s_add_i32 s98, s98, 0x20000
	v_lshl_add_u32 v66, v64, 3, s98
	v_lshlrev_b32_e32 v67, 3, v64
	v_add_u32_e32 v67, 0x20000, v67
	s_mul_i32 s99, s70, 0x880
	v_lshl_add_u32 v68, v64, 2, s99
	s_lshr_b32 s98, s70, 1
	s_lshl_b32 s98, s98, 12
	s_and_b32 s99, s70, 1
	s_lshl_b32 s99, s99, 8
	s_add_i32 s98, s98, s99
	v_lshrrev_b32_e32 v69, 4, v64
	v_lshlrev_b32_e32 v69, 9, v69
	v_and_b32_e32 v70, 15, v64
	v_lshl_add_u32 v69, v70, 2, v69
	v_add_u32_e32 v69, s98, v69
	s_waitcnt lgkmcnt(7)
	v_add_f32_e32 v170, 0, v170
	v_add_f32_e32 v171, 0, v171
	s_waitcnt lgkmcnt(6)
	v_add_f32_e32 v172, v170, v172
	v_add_f32_e32 v173, v171, v173
	s_waitcnt lgkmcnt(5)
	v_add_f32_e32 v174, v172, v174
	v_add_f32_e32 v175, v173, v175
	s_waitcnt lgkmcnt(4)
	v_add_f32_e32 v176, v174, v176
	v_add_f32_e32 v177, v175, v177
	s_waitcnt lgkmcnt(3)
	v_add_f32_e32 v178, v176, v178
	v_add_f32_e32 v179, v177, v179
	s_waitcnt lgkmcnt(2)
	v_add_f32_e32 v180, v178, v180
	v_add_f32_e32 v181, v179, v181
	s_waitcnt lgkmcnt(1)
	v_add_f32_e32 v182, v180, v182
	v_add_f32_e32 v183, v181, v183
	s_waitcnt lgkmcnt(0)
	v_add_f32_e32 v184, v182, v184
	v_add_f32_e32 v185, v183, v185
	ds_write_b64 v66, v[184:185]
	s_waitcnt lgkmcnt(0)
	s_barrier
	ds_read_b64 v[72:73], v67
	ds_read_b64 v[74:75], v67 offset:512
	ds_read_b64 v[76:77], v67 offset:1024
	ds_read_b64 v[78:79], v67 offset:1536
	ds_read_b64 v[80:81], v67 offset:2048
	ds_read_b64 v[82:83], v67 offset:2560
	ds_read_b64 v[84:85], v67 offset:3072
	ds_read_b64 v[86:87], v67 offset:3584
	ds_read_b32 v202, v68
	ds_read_b32 v210, v68 offset:17408
	ds_read_b32 v203, v68 offset:272
	ds_read_b32 v211, v68 offset:17680
	ds_read_b32 v204, v68 offset:544
	ds_read_b32 v212, v68 offset:17952
	s_waitcnt lgkmcnt(6)
	ds_read_b32 v205, v68 offset:816
	ds_read_b32 v213, v68 offset:18224
	ds_read_b32 v206, v68 offset:1088
	ds_read_b32 v214, v68 offset:18496
	ds_read_b32 v207, v68 offset:1360
	ds_read_b32 v215, v68 offset:18768
	ds_read_b32 v208, v68 offset:1632
	ds_read_b32 v216, v68 offset:19040
	v_mul_f32_e32 v88, v238, v72
	v_mul_f32_e32 v89, v238, v73
	v_fmac_f32_e32 v88, v239, v74
	v_fmac_f32_e32 v89, v239, v75
	v_fmac_f32_e32 v88, v240, v76
	v_fmac_f32_e32 v89, v240, v77
	v_fmac_f32_e32 v88, v241, v78
	v_fmac_f32_e32 v89, v241, v79
	v_fmac_f32_e32 v88, v242, v80
	v_fmac_f32_e32 v89, v242, v81
	v_fmac_f32_e32 v88, v243, v82
	v_fmac_f32_e32 v89, v243, v83
	v_fmac_f32_e32 v88, v244, v84
	v_fmac_f32_e32 v89, v244, v85
	v_add_f32_e32 v90, v72, v74
	v_add_f32_e32 v91, v73, v75
	v_add_f32_e32 v90, v90, v76
	v_add_f32_e32 v91, v91, v77
	v_add_f32_e32 v90, v90, v78
	v_add_f32_e32 v91, v91, v79
	v_add_f32_e32 v90, v90, v80
	v_add_f32_e32 v91, v91, v81
	v_add_f32_e32 v90, v90, v82
	v_add_f32_e32 v91, v91, v83
	v_add_f32_e32 v90, v90, v84
	v_add_f32_e32 v91, v91, v85
	v_add_f32_e32 v90, v90, v86
	v_add_f32_e32 v91, v91, v87
	v_mul_f32_e32 v92, 0x3fb8aa3b, v90
	v_mul_f32_e32 v93, 0x3fb8aa3b, v91
	v_exp_f32_e32 v92, v92
	v_exp_f32_e32 v93, v93
	v_add_f32_e32 v170, v170, v88
	v_add_f32_e32 v171, v171, v89
	v_add_f32_e32 v172, v172, v88
	v_add_f32_e32 v173, v173, v89
	v_add_f32_e32 v174, v174, v88
	v_add_f32_e32 v175, v175, v89
	v_add_f32_e32 v176, v176, v88
	v_add_f32_e32 v177, v177, v89
	v_add_f32_e32 v178, v178, v88
	v_add_f32_e32 v179, v179, v89
	v_add_f32_e32 v180, v180, v88
	v_add_f32_e32 v181, v181, v89
	v_add_f32_e32 v182, v182, v88
	v_add_f32_e32 v183, v183, v89
	v_add_f32_e32 v184, v184, v88
	v_add_f32_e32 v185, v185, v89
	v_mul_f32_e32 v170, 0x3fb8aa3b, v170
	v_mul_f32_e32 v171, 0x3fb8aa3b, v171
	v_mul_f32_e32 v172, 0x3fb8aa3b, v172
	v_mul_f32_e32 v173, 0x3fb8aa3b, v173
	v_mul_f32_e32 v174, 0x3fb8aa3b, v174
	v_mul_f32_e32 v175, 0x3fb8aa3b, v175
	v_mul_f32_e32 v176, 0x3fb8aa3b, v176
	v_mul_f32_e32 v177, 0x3fb8aa3b, v177
	v_mul_f32_e32 v178, 0x3fb8aa3b, v178
	v_mul_f32_e32 v179, 0x3fb8aa3b, v179
	v_mul_f32_e32 v180, 0x3fb8aa3b, v180
	v_mul_f32_e32 v181, 0x3fb8aa3b, v181
	v_mul_f32_e32 v182, 0x3fb8aa3b, v182
	v_mul_f32_e32 v183, 0x3fb8aa3b, v183
	v_mul_f32_e32 v184, 0x3fb8aa3b, v184
	v_mul_f32_e32 v185, 0x3fb8aa3b, v185
	v_exp_f32_e32 v170, v170
	v_exp_f32_e32 v171, v171
	v_exp_f32_e32 v172, v172
	v_exp_f32_e32 v173, v173
	v_exp_f32_e32 v174, v174
	v_exp_f32_e32 v175, v175
	v_exp_f32_e32 v176, v176
	v_exp_f32_e32 v177, v177
	v_exp_f32_e32 v178, v178
	v_exp_f32_e32 v179, v179
	v_exp_f32_e32 v180, v180
	v_exp_f32_e32 v181, v181
	v_exp_f32_e32 v182, v182
	v_exp_f32_e32 v183, v183
	v_exp_f32_e32 v184, v184
	v_exp_f32_e32 v185, v185
	v_rcp_f32_e32 v186, v170
	v_rcp_f32_e32 v187, v171
	v_rcp_f32_e32 v188, v172
	v_rcp_f32_e32 v189, v173
	v_rcp_f32_e32 v190, v174
	v_rcp_f32_e32 v191, v175
	v_rcp_f32_e32 v192, v176
	v_rcp_f32_e32 v193, v177
	v_rcp_f32_e32 v194, v178
	v_rcp_f32_e32 v195, v179
	v_rcp_f32_e32 v196, v180
	v_rcp_f32_e32 v197, v181
	v_rcp_f32_e32 v198, v182
	v_rcp_f32_e32 v199, v183
	v_rcp_f32_e32 v200, v184
	v_rcp_f32_e32 v201, v185
	v_mul_f32_e32 v170, 0x3db504f3, v170
	v_mul_f32_e32 v171, 0x3db504f3, v171
	v_mul_f32_e32 v172, 0x3db504f3, v172
	v_mul_f32_e32 v173, 0x3db504f3, v173
	v_mul_f32_e32 v174, 0x3db504f3, v174
	v_mul_f32_e32 v175, 0x3db504f3, v175
	v_mul_f32_e32 v176, 0x3db504f3, v176
	v_mul_f32_e32 v177, 0x3db504f3, v177
	v_mul_f32_e32 v178, 0x3db504f3, v178
	v_mul_f32_e32 v179, 0x3db504f3, v179
	v_mul_f32_e32 v180, 0x3db504f3, v180
	v_mul_f32_e32 v181, 0x3db504f3, v181
	v_mul_f32_e32 v182, 0x3db504f3, v182
	v_mul_f32_e32 v183, 0x3db504f3, v183
	v_mul_f32_e32 v184, 0x3db504f3, v184
	v_mul_f32_e32 v185, 0x3db504f3, v185
	s_cmp_lg_u32 s70, 0
	s_cbranch_scc1 .Lscan_c2_nodl
	v_lshlrev_b32_e32 v70, 3, v64
	v_add_u32_e32 v70, 0x1fc00, v70
	ds_write_b64 v70, v[92:93]
; __device__ __forceinline__ int v_st(int k, int c) { const int kk = (k & ~0xC) | ((k & 4) << 1) | ((k & 8) >> 1); return ((kk >> 3) * 4 + (c >> 5)) * 512 + ((kk & 7) * 32 + (c & 31)) * 2; }
; __device__ __forceinline__ float bf2f(short s) { return __uint_as_float(((unsigned)(unsigned short)s) << 16); }
; __device__ __forceinline__ float bf2f(u16 u) { return __uint_as_float((unsigned)u << 16); }
; __device__ __forceinline__ u16 f2bf(float f) { return (u16)(pk2(f, 0.f) & 0xffffu); }
; __device__ __forceinline__ void scan_unit(const int unit, const Args& a, unsigned char* lds, const int mk_wid) {
;     ...
;           u16* qcol = qe + (g * 16) * QP + c; u16* kcol = ke + (g * 16) * QP + c; unsigned char* kdb = lds + L_KD + v_st(g * 16, c);
; #pragma unroll
;           for (int ii = 0; ii < 16; ++ii) { const float bb = bl[ii] + off;
;               const float qf = bf2f(qcol[ii * QP]), kf = bf2f(kcol[ii * QP]);
;               const float e = __builtin_amdgcn_exp2f(bb * 1.4426950408889634f), ker = kf * __builtin_amdgcn_rcpf(e);
;               qcol[ii * QP] = f2bf(qf * (0.088388347648318440f * e));
;               kcol[ii * QP] = f2bf(ker);
;               *(u16*)(kdb + v_st(ii, 0)) = f2bf(ker * dlc); } }
.Lscan_c2_nodl:
	v_mov_b32_e32 v71, 0xffff0000
	s_waitcnt lgkmcnt(12)
	v_lshlrev_b32_e32 v218, 16, v202
	v_and_b32_e32 v219, v71, v202
	v_lshlrev_b32_e32 v220, 16, v210
	v_and_b32_e32 v221, v71, v210
	v_mul_f32_e32 v218, v170, v218
	v_mul_f32_e32 v219, v171, v219
	v_mul_f32_e32 v220, v186, v220
	v_mul_f32_e32 v221, v187, v221
	v_cvt_pk_bf16_f32 v224, v218, v219
	v_mul_f32_e32 v222, v92, v220
	v_mul_f32_e32 v223, v93, v221
	v_cvt_pk_bf16_f32 v225, v220, v221
	ds_write_b32 v68, v224
	ds_write_b32 v68, v225 offset:17408
	v_cvt_pk_bf16_f32 v226, v222, v223
	ds_read_b32 v209, v68 offset:1904
	ds_read_b32 v217, v68 offset:19312
	ds_write_b32 v69, v226 offset:34816
	s_waitcnt lgkmcnt(15)
	v_lshlrev_b32_e32 v228, 16, v203
	v_and_b32_e32 v229, v71, v203
	v_lshlrev_b32_e32 v230, 16, v211
	v_and_b32_e32 v231, v71, v211
	v_mul_f32_e32 v228, v172, v228
	v_mul_f32_e32 v229, v173, v229
	v_mul_f32_e32 v230, v188, v230
	v_mul_f32_e32 v231, v189, v231
	v_cvt_pk_bf16_f32 v234, v228, v229
	v_mul_f32_e32 v232, v92, v230
	v_mul_f32_e32 v233, v93, v231
	v_cvt_pk_bf16_f32 v235, v230, v231
	ds_write_b32 v68, v234 offset:272
	ds_write_b32 v68, v235 offset:17680
	v_cvt_pk_bf16_f32 v236, v232, v233
	ds_write_b32 v69, v236 offset:34880
	s_waitcnt lgkmcnt(15)
	v_lshlrev_b32_e32 v218, 16, v204
	v_and_b32_e32 v219, v71, v204
	v_lshlrev_b32_e32 v220, 16, v212
	v_and_b32_e32 v221, v71, v212
	v_mul_f32_e32 v218, v174, v218
	v_mul_f32_e32 v219, v175, v219
	v_mul_f32_e32 v220, v190, v220
	v_mul_f32_e32 v221, v191, v221
	v_cvt_pk_bf16_f32 v224, v218, v219
	v_mul_f32_e32 v222, v92, v220
	v_mul_f32_e32 v223, v93, v221
	v_cvt_pk_bf16_f32 v225, v220, v221
	ds_write_b32 v68, v224 offset:544
	ds_write_b32 v68, v225 offset:17952
	v_cvt_pk_bf16_f32 v226, v222, v223
	ds_write_b32 v69, v226 offset:34944
	s_waitcnt lgkmcnt(15)
	v_lshlrev_b32_e32 v228, 16, v205
	v_and_b32_e32 v229, v71, v205
	v_lshlrev_b32_e32 v230, 16, v213
	v_and_b32_e32 v231, v71, v213
	v_mul_f32_e32 v228, v176, v228
	v_mul_f32_e32 v229, v177, v229
	v_mul_f32_e32 v230, v192, v230
	v_mul_f32_e32 v231, v193, v231
	v_cvt_pk_bf16_f32 v234, v228, v229
	v_mul_f32_e32 v232, v92, v230
	v_mul_f32_e32 v233, v93, v231
	v_cvt_pk_bf16_f32 v235, v230, v231
	ds_write_b32 v68, v234 offset:816
	ds_write_b32 v68, v235 offset:18224
	v_cvt_pk_bf16_f32 v236, v232, v233
	ds_write_b32 v69, v236 offset:35008
	s_waitcnt lgkmcnt(15)
	v_lshlrev_b32_e32 v218, 16, v206
	v_and_b32_e32 v219, v71, v206
	v_lshlrev_b32_e32 v220, 16, v214
	v_and_b32_e32 v221, v71, v214
	v_mul_f32_e32 v218, v178, v218
	v_mul_f32_e32 v219, v179, v219
	v_mul_f32_e32 v220, v194, v220
	v_mul_f32_e32 v221, v195, v221
	v_cvt_pk_bf16_f32 v224, v218, v219
	v_mul_f32_e32 v222, v92, v220
	v_mul_f32_e32 v223, v93, v221
	v_cvt_pk_bf16_f32 v225, v220, v221
	ds_write_b32 v68, v224 offset:1088
	ds_write_b32 v68, v225 offset:18496
	v_cvt_pk_bf16_f32 v226, v222, v223
	ds_write_b32 v69, v226 offset:36864
	s_waitcnt lgkmcnt(15)
	v_lshlrev_b32_e32 v228, 16, v207
	v_and_b32_e32 v229, v71, v207
	v_lshlrev_b32_e32 v230, 16, v215
	v_and_b32_e32 v231, v71, v215
	v_mul_f32_e32 v228, v180, v228
	v_mul_f32_e32 v229, v181, v229
	v_mul_f32_e32 v230, v196, v230
	v_mul_f32_e32 v231, v197, v231
	v_cvt_pk_bf16_f32 v234, v228, v229
	v_mul_f32_e32 v232, v92, v230
	v_mul_f32_e32 v233, v93, v231
	v_cvt_pk_bf16_f32 v235, v230, v231
	ds_write_b32 v68, v234 offset:1360
	ds_write_b32 v68, v235 offset:18768
	v_cvt_pk_bf16_f32 v236, v232, v233
	ds_write_b32 v69, v236 offset:36928
	s_waitcnt lgkmcnt(15)
	v_lshlrev_b32_e32 v218, 16, v208
	v_and_b32_e32 v219, v71, v208
	v_lshlrev_b32_e32 v220, 16, v216
	v_and_b32_e32 v221, v71, v216
	v_mul_f32_e32 v218, v182, v218
	v_mul_f32_e32 v219, v183, v219
	v_mul_f32_e32 v220, v198, v220
	v_mul_f32_e32 v221, v199, v221
	v_cvt_pk_bf16_f32 v224, v218, v219
	v_mul_f32_e32 v222, v92, v220
	v_mul_f32_e32 v223, v93, v221
	v_cvt_pk_bf16_f32 v225, v220, v221
	ds_write_b32 v68, v224 offset:1632
	ds_write_b32 v68, v225 offset:19040
	v_cvt_pk_bf16_f32 v226, v222, v223
	ds_write_b32 v69, v226 offset:36992
	s_waitcnt lgkmcnt(15)
	v_lshlrev_b32_e32 v228, 16, v209
	v_and_b32_e32 v229, v71, v209
	v_lshlrev_b32_e32 v230, 16, v217
	v_and_b32_e32 v231, v71, v217
	v_mul_f32_e32 v228, v184, v228
	v_mul_f32_e32 v229, v185, v229
	v_mul_f32_e32 v230, v200, v230
	v_mul_f32_e32 v231, v201, v231
	v_cvt_pk_bf16_f32 v234, v228, v229
	v_mul_f32_e32 v232, v92, v230
	v_mul_f32_e32 v233, v93, v231
	v_cvt_pk_bf16_f32 v235, v230, v231
	ds_write_b32 v68, v234 offset:1904
	ds_write_b32 v68, v235 offset:19312
	v_cvt_pk_bf16_f32 v236, v232, v233
	ds_write_b32 v69, v236 offset:37056
	s_add_i32 s58, s5, 1
	s_cmp_eq_u32 s50, 3
	s_cbranch_scc1 .LBB0_435
	v_mbcnt_lo_u32_b32 v64, -1, 0
	v_mbcnt_hi_u32_b32 v64, -1, v64
	s_andn2_b64 vcc, exec, s[6:7]
	v_add_u32_e32 v70, s72, v64
	s_mov_b32 s34, s58
	s_cbranch_vccnz .LBB0_426
	s_cmp_gt_u32 s5, 2
	s_mov_b32 s34, s50
	s_cbranch_scc1 .LBB0_426
	s_sub_i32 s34, 2, s5

; __device__ __forceinline__ unsigned pk2(float lo, float hi) { f32x2_t v = {lo, hi}; bf16x2_t b = __builtin_convertvector(v, bf16x2_t); return __builtin_bit_cast(unsigned, b); }
; __device__ __forceinline__ void scan_unit(const int unit, const Args& a, unsigned char* lds, const int mk_wid) {
;     ...
;               f32x16 o0 = f32x16{}, o1 = f32x16{};
; #pragma unroll
;               for (int ct = 0; ct < 4; ++ct)
; #pragma unroll
;                 for (int kb = 0; kb < 2; ++kb) { const int cb = ct * 32 + kb * 16;
;                     v4u sw; sw.x = pk2(S[ct][8 * kb + 0], S[ct][8 * kb + 1]); sw.y = pk2(S[ct][8 * kb + 2], S[ct][8 * kb + 3]); sw.z = pk2(S[ct][8 * kb + 4], S[ct][8 * kb + 5]); sw.w = pk2(S[ct][8 * kb + 6], S[ct][8 * kb + 7]);
;                     const bf16x8 sb = __builtin_bit_cast(bf16x8, sw);
;                     { const u16* p0 = qe + r32 * QP + cb + 4 * hi; const v2u lo = *(const v2u*)p0, hh = *(const v2u*)(p0 + 8); v4u aw = {lo.x, lo.y, hh.x, hh.y};
;                       o0 = __builtin_amdgcn_mfma_f32_32x32x16_bf16(__builtin_bit_cast(bf16x8, aw), sb, o0, 0, 0, 0); }
;                     { const u16* p1 = qe + (32 + r32) * QP + cb + 4 * hi; const v2u lo = *(const v2u*)p1, hh = *(const v2u*)(p1 + 8); v4u aw = {lo.x, lo.y, hh.x, hh.y};
;                       o1 = __builtin_amdgcn_mfma_f32_32x32x16_bf16(__builtin_bit_cast(bf16x8, aw), sb, o1, 0, 0, 0); } }
.LBB0_442:
	v_and_b32_e32 v168, 31, v64
	v_mul_u32_u24_e32 v64, 0x110, v168
	v_lshlrev_b32_e32 v65, 3, v157
	v_add3_u32 v144, 0, v64, v65
	v_add_u32_e32 v145, 0x2000, v144
	ds_read2_b64 v[170:173], v144 offset1:2
	ds_read2_b64 v[174:177], v144 offset0:4 offset1:6
	ds_read2_b64 v[178:181], v145 offset0:64 offset1:66
	ds_read2_b64 v[182:185], v145 offset0:68 offset1:70
	ds_read2_b64 v[186:189], v144 offset0:8 offset1:10
	ds_read2_b64 v[190:193], v145 offset0:72 offset1:74
	ds_read2_b64 v[194:197], v144 offset0:12 offset1:14
	ds_read2_b64 v[198:201], v145 offset0:76 offset1:78
	ds_read2_b64 v[202:205], v144 offset0:16 offset1:18
	ds_read2_b64 v[206:209], v145 offset0:80 offset1:82
	ds_read2_b64 v[210:213], v144 offset0:20 offset1:22
	ds_read2_b64 v[214:217], v145 offset0:84 offset1:86
	ds_read2_b64 v[218:221], v144 offset0:24 offset1:26
	ds_read2_b64 v[222:225], v145 offset0:88 offset1:90
	ds_read2_b64 v[226:229], v144 offset0:28 offset1:30
	v_cvt_pk_bf16_f32 v80, v0, v1
	v_cvt_pk_bf16_f32 v81, v2, v3
	v_cvt_pk_bf16_f32 v82, v4, v5
	v_cvt_pk_bf16_f32 v83, v6, v7
	s_waitcnt lgkmcnt(14)
	s_nop 0
	v_mfma_f32_32x32x16_bf16 v[64:79], v[170:173], v[80:83], 0
	ds_read2_b64 v[230:233], v145 offset0:92 offset1:94
	v_cvt_pk_bf16_f32 v140, v8, v9
	v_cvt_pk_bf16_f32 v141, v10, v11
	v_cvt_pk_bf16_f32 v142, v12, v13
	v_cvt_pk_bf16_f32 v143, v14, v15
	v_cvt_pk_bf16_f32 v160, v56, v57
	v_cvt_pk_bf16_f32 v161, v58, v59
	v_cvt_pk_bf16_f32 v162, v60, v61
	v_cvt_pk_bf16_f32 v163, v62, v63
	s_waitcnt lgkmcnt(14)
	s_nop 0
	v_mfma_f32_32x32x16_bf16 v[64:79], v[174:177], v[140:143], v[64:79]
	s_waitcnt lgkmcnt(13)
	v_mfma_f32_32x32x16_bf16 v[80:95], v[178:181], v[80:83], 0
	s_waitcnt lgkmcnt(12)
	v_mfma_f32_32x32x16_bf16 v[80:95], v[182:185], v[140:143], v[80:95]
	v_cvt_pk_bf16_f32 v140, v16, v17
	v_cvt_pk_bf16_f32 v141, v18, v19
	v_cvt_pk_bf16_f32 v142, v20, v21
	v_cvt_pk_bf16_f32 v143, v22, v23
	s_waitcnt lgkmcnt(11)
	s_nop 0
	v_mfma_f32_32x32x16_bf16 v[64:79], v[186:189], v[140:143], v[64:79]
	s_waitcnt lgkmcnt(10)
	v_mfma_f32_32x32x16_bf16 v[80:95], v[190:193], v[140:143], v[80:95]
	v_cvt_pk_bf16_f32 v140, v24, v25
	v_cvt_pk_bf16_f32 v141, v26, v27
	v_cvt_pk_bf16_f32 v142, v28, v29
	v_cvt_pk_bf16_f32 v143, v30, v31
	s_waitcnt lgkmcnt(9)
	s_nop 0
	v_mfma_f32_32x32x16_bf16 v[64:79], v[194:197], v[140:143], v[64:79]
	s_waitcnt lgkmcnt(8)
	v_mfma_f32_32x32x16_bf16 v[80:95], v[198:201], v[140:143], v[80:95]
	v_cvt_pk_bf16_f32 v140, v32, v33
	v_cvt_pk_bf16_f32 v141, v34, v35
	v_cvt_pk_bf16_f32 v142, v36, v37
	v_cvt_pk_bf16_f32 v143, v38, v39
	s_waitcnt lgkmcnt(7)
	s_nop 0
	v_mfma_f32_32x32x16_bf16 v[64:79], v[202:205], v[140:143], v[64:79]
	s_waitcnt lgkmcnt(6)
	v_mfma_f32_32x32x16_bf16 v[80:95], v[206:209], v[140:143], v[80:95]
	v_cvt_pk_bf16_f32 v140, v40, v41
	v_cvt_pk_bf16_f32 v141, v42, v43
	v_cvt_pk_bf16_f32 v142, v44, v45
	v_cvt_pk_bf16_f32 v143, v46, v47
	s_waitcnt lgkmcnt(5)
	s_nop 0
	v_mfma_f32_32x32x16_bf16 v[64:79], v[210:213], v[140:143], v[64:79]
	s_waitcnt lgkmcnt(4)
	v_mfma_f32_32x32x16_bf16 v[80:95], v[214:217], v[140:143], v[80:95]
	v_cvt_pk_bf16_f32 v140, v48, v49
	v_cvt_pk_bf16_f32 v141, v50, v51
	v_cvt_pk_bf16_f32 v142, v52, v53
	v_cvt_pk_bf16_f32 v143, v54, v55
	s_waitcnt lgkmcnt(3)
	s_nop 0
	v_mfma_f32_32x32x16_bf16 v[64:79], v[218:221], v[140:143], v[64:79]
	s_waitcnt lgkmcnt(2)
	v_mfma_f32_32x32x16_bf16 v[80:95], v[222:225], v[140:143], v[80:95]
	ds_read_b64_tr_b16 v[136:137], v158 offset:0
	s_waitcnt lgkmcnt(2)
; __device__ __forceinline__ int crow(int r, int hi) { return (r & 3) + 8 * (r >> 2) + 4 * hi; }
; __device__ __forceinline__ u16 f2bf(float f) { return (u16)(pk2(f, 0.f) & 0xffffu); }
; #define GLA_SBAR() __builtin_amdgcn_sched_barrier(0)
; #define GLA_LOADV() do { vl0 = tr_read<v_rd_off(0, 0, 0)>(vb); vh0 = tr_read<v_rd_off(0, 0, 1)>(vb); vl1 = tr_read<v_rd_off(0, 1, 0)>(vb); vh1 = tr_read<v_rd_off(0, 1, 1)>(vb); \
;               vl2 = tr_read<v_rd_off(0, 2, 0)>(vb); vh2 = tr_read<v_rd_off(0, 2, 1)>(vb); vl3 = tr_read<v_rd_off(0, 3, 0)>(vb); vh3 = tr_read<v_rd_off(0, 3, 1)>(vb); } while (0)
; __device__ __forceinline__ void scan_unit(const int unit, const Args& a, unsigned char* lds, const int mk_wid) {
;     ...
;               GLA_LOADV();
;               asm volatile("s_waitcnt lgkmcnt(0)" ::: "memory"); GLA_SBAR();
;               { const u16* a0 = am + r32 * AP + hi * 8; const u16* a1 = am + (32 + r32) * AP + hi * 8;
;                 o0 = __builtin_amdgcn_mfma_f32_32x32x16_bf16(*(const bf16x8*)(a0), GLA_PK(vl0, vh0), o0, 0, 0, 0);
;                 o0 = __builtin_amdgcn_mfma_f32_32x32x16_bf16(*(const bf16x8*)(a0 + 16), GLA_PK(vl1, vh1), o0, 0, 0, 0);
;                 o1 = __builtin_amdgcn_mfma_f32_32x32x16_bf16(*(const bf16x8*)(a1), GLA_PK(vl0, vh0), o1, 0, 0, 0);
;                 o1 = __builtin_amdgcn_mfma_f32_32x32x16_bf16(*(const bf16x8*)(a1 + 16), GLA_PK(vl1, vh1), o1, 0, 0, 0);
;                 o1 = __builtin_amdgcn_mfma_f32_32x32x16_bf16(*(const bf16x8*)(a1 + 32), GLA_PK(vl2, vh2), o1, 0, 0, 0);
;                 o1 = __builtin_amdgcn_mfma_f32_32x32x16_bf16(*(const bf16x8*)(a1 + 48), GLA_PK(vl3, vh3), o1, 0, 0, 0); }
;               { u16* ow = ot + (4 * hi) * 256 + vt * 32 + r32;
; #pragma unroll
;                 for (int r = 0; r < 16; ++r) { const int i0 = crow(r, 0); ow[i0 * 256] = f2bf(o0[r]); ow[(i0 + 32) * 256] = f2bf(o1[r]); } }
	v_mfma_f32_32x32x16_bf16 v[64:79], v[226:229], v[160:163], v[64:79]
	ds_read_b64_tr_b16 v[138:139], v158 offset:0x800
	ds_read_b64_tr_b16 v[140:141], v158 offset:0x1000
	ds_read_b64_tr_b16 v[142:143], v158 offset:0x1800
	ds_read_b64_tr_b16 v[144:145], v158 offset:0x2000
	ds_read_b64_tr_b16 v[146:147], v158 offset:0x2800
	ds_read_b64_tr_b16 v[148:149], v158 offset:0x3000
	ds_read_b64_tr_b16 v[150:151], v158 offset:0x3800
	s_waitcnt lgkmcnt(0)
	v_mfma_f32_32x32x16_bf16 v[80:95], v[230:233], v[160:163], v[80:95]
	v_mul_u32_u24_e32 v158, 0x90, v168
	v_lshlrev_b32_e32 v159, 4, v157
	v_add3_u32 v166, s57, v158, v159
	ds_read_b128 v[158:161], v166
	ds_read_b128 v[162:165], v166 offset:32
	s_mov_b32 s34, s42
	s_waitcnt lgkmcnt(1)
	v_mfma_f32_32x32x16_bf16 v[64:79], v[158:161], v[136:139], v[64:79]
	s_waitcnt lgkmcnt(0)
	v_mfma_f32_32x32x16_bf16 v[64:79], v[162:165], v[140:143], v[64:79]
	ds_read_b128 v[158:161], v166 offset:4608
	ds_read_b128 v[162:165], v166 offset:4640
	s_waitcnt lgkmcnt(1)
	v_mfma_f32_32x32x16_bf16 v[80:95], v[158:161], v[136:139], v[80:95]
	s_nop 7
	v_cvt_pk_bf16_f32 v64, v64, s0
	s_waitcnt lgkmcnt(0)
	v_mfma_f32_32x32x16_bf16 v[80:95], v[162:165], v[140:143], v[80:95]
	ds_read_b128 v[158:161], v166 offset:4672
	ds_read_b128 v[162:165], v166 offset:4704
	s_waitcnt lgkmcnt(1)
	v_mfma_f32_32x32x16_bf16 v[80:95], v[158:161], v[144:147], v[80:95]
	v_lshlrev_b32_e32 v158, 11, v157
	v_lshlrev_b32_e32 v159, 1, v168
	v_add3_u32 v158, s49, v158, v159
	ds_write_b16 v158, v64
	s_waitcnt lgkmcnt(1)
	v_mfma_f32_32x32x16_bf16 v[80:95], v[162:165], v[148:151], v[80:95]
	s_nop 11
	v_cvt_pk_bf16_f32 v64, v80, s0
	ds_write_b16 v158, v64 offset:16384
	v_cvt_pk_bf16_f32 v64, v65, s0
	ds_write_b16 v158, v64 offset:512
	v_cvt_pk_bf16_f32 v64, v81, s0
	ds_write_b16 v158, v64 offset:16896
	v_cvt_pk_bf16_f32 v64, v66, s0
	ds_write_b16 v158, v64 offset:1024
	v_cvt_pk_bf16_f32 v64, v82, s0
	ds_write_b16 v158, v64 offset:17408
	v_cvt_pk_bf16_f32 v64, v67, s0
	ds_write_b16 v158, v64 offset:1536
	v_cvt_pk_bf16_f32 v64, v83, s0
	ds_write_b16 v158, v64 offset:17920
	v_cvt_pk_bf16_f32 v64, v68, s0
	ds_write_b16 v158, v64 offset:4096
	v_cvt_pk_bf16_f32 v64, v84, s0
	ds_write_b16 v158, v64 offset:20480
	v_cvt_pk_bf16_f32 v64, v69, s0
	ds_write_b16 v158, v64 offset:4608
	v_cvt_pk_bf16_f32 v64, v85, s0
	ds_write_b16 v158, v64 offset:20992
	v_cvt_pk_bf16_f32 v64, v70, s0
	ds_write_b16 v158, v64 offset:5120
	v_cvt_pk_bf16_f32 v64, v86, s0
	ds_write_b16 v158, v64 offset:21504
	v_cvt_pk_bf16_f32 v64, v71, s0
	ds_write_b16 v158, v64 offset:5632
	v_cvt_pk_bf16_f32 v64, v87, s0
	ds_write_b16 v158, v64 offset:22016
	v_cvt_pk_bf16_f32 v64, v72, s0
	ds_write_b16 v158, v64 offset:8192
	v_cvt_pk_bf16_f32 v64, v88, s0
	ds_write_b16 v158, v64 offset:24576
	v_cvt_pk_bf16_f32 v64, v73, s0
	ds_write_b16 v158, v64 offset:8704
	v_cvt_pk_bf16_f32 v64, v89, s0
	ds_write_b16 v158, v64 offset:25088
	v_cvt_pk_bf16_f32 v64, v74, s0
	ds_write_b16 v158, v64 offset:9216
	v_cvt_pk_bf16_f32 v64, v90, s0
	ds_write_b16 v158, v64 offset:25600
	v_cvt_pk_bf16_f32 v64, v75, s0
	ds_write_b16 v158, v64 offset:9728
	v_cvt_pk_bf16_f32 v64, v91, s0
	ds_write_b16 v158, v64 offset:26112
	v_cvt_pk_bf16_f32 v64, v76, s0
	ds_write_b16 v158, v64 offset:12288
	v_cvt_pk_bf16_f32 v64, v92, s0
	ds_write_b16 v158, v64 offset:28672
	v_cvt_pk_bf16_f32 v64, v77, s0
	ds_write_b16 v158, v64 offset:12800
	v_cvt_pk_bf16_f32 v64, v93, s0
	ds_write_b16 v158, v64 offset:29184
	v_cvt_pk_bf16_f32 v64, v78, s0
	ds_write_b16 v158, v64 offset:13312
	v_cvt_pk_bf16_f32 v64, v94, s0
	ds_write_b16 v158, v64 offset:29696
	v_cvt_pk_bf16_f32 v64, v79, s0
	ds_write_b16 v158, v64 offset:13824
	v_cvt_pk_bf16_f32 v64, v95, s0
	ds_write_b16 v158, v64 offset:30208

; __device__ __forceinline__ float bf2f(short s) { return __uint_as_float(((unsigned)(unsigned short)s) << 16); }
; __device__ __forceinline__ float bf2f(u16 u) { return __uint_as_float((unsigned)u << 16); }
; __device__ __forceinline__ unsigned pk2(float lo, float hi) { f32x2_t v = {lo, hi}; bf16x2_t b = __builtin_convertvector(v, bf16x2_t); return __builtin_bit_cast(unsigned, b); }
; __device__ __forceinline__ float sigmoidf_(float x) { return __builtin_amdgcn_rcpf(1.f + __expf(-x)); }
;     __device__ __forceinline__ void operator()(const pg8::f32x4 (&acc)[2][2][4][2], const pg8::Unit& u, int wr, int wc, int fr, int fq) const {
;     ...
;             for (int m = 0; m < 4; ++m) { const size_t row = (size_t)u.pm * 256 + ai * 128 + wr * 64 + m * 16 + fr;
; #pragma unroll
;                 for (int bj = 0; bj < 2; ++bj) { const int col = col0 + bj * 128;
;                     gwv[m][bj] = __builtin_nontemporal_load((const v4u*)(MG + row * 2048 + MODE * 1024 + col));
;                     twv[m][bj] = (MODE == 1) ? __builtin_nontemporal_load((const v4u*)(T1 + row * 1024 + col)) : (v4u){0u, 0u, 0u, 0u}; } }
; #pragma unroll
;             for (int m = 0; m < 4; ++m) { const size_t row = (size_t)u.pm * 256 + ai * 128 + wr * 64 + m * 16 + fr;
; #pragma unroll
;                 for (int bj = 0; bj < 2; ++bj) { const int col = col0 + bj * 128;
;                     const pg8::f32x4 v0 = acc[ai][bj][m][0], v1 = acc[ai][bj][m][1];
;                     const float r[8] = {v0[0], v0[1], v0[2], v0[3], v1[0], v1[1], v1[2], v1[3]};
;                     const unsigned gws[4] = {gwv[m][bj].x, gwv[m][bj].y, gwv[m][bj].z, gwv[m][bj].w};
;                     const unsigned tws[4] = {twv[m][bj].x, twv[m][bj].y, twv[m][bj].z, twv[m][bj].w};
;                     unsigned ow[4];
; #pragma unroll
;                     for (int e = 0; e < 4; ++e) {
;                         float a0 = sigmoidf_(bf2f((u16)(gws[e] & 0xffffu))) * r[2 * e], a1 = sigmoidf_(bf2f((u16)(gws[e] >> 16))) * r[2 * e + 1];
;                         if (MODE == 1) { a0 += bf2f((u16)(tws[e] & 0xffffu)); a1 += bf2f((u16)(tws[e] >> 16)); }
;                         ow[e] = pk2(a0, a1); }
;                     v4u w = {ow[0], ow[1], ow[2], ow[3]};
;                     *(v4u*)((MODE == 0 ? T1 : MRG) + row * 1024 + col) = w; } }
.LBB0_652:
	v_lshl_or_b32 v128, s35, 8, v205
	s_ashr_i32 s35, s34, 31
	s_lshl_b64 s[34:35], s[34:35], 8
	v_lshl_add_u64 v[196:197], s[34:35], 0, v[184:185]
	v_ashrrev_i32_e32 v129, 31, v128
	v_lshlrev_b64 v[130:131], 12, v[196:197]
	v_lshl_add_u64 v[130:131], s[14:15], 0, v[130:131]
	v_lshlrev_b64 v[226:227], 11, v[196:197]
	v_lshlrev_b64 v[194:195], 1, v[128:129]
	v_lshl_add_u64 v[132:133], s[6:7], 0, v[226:227]
	v_lshl_add_u64 v[128:129], v[130:131], 0, v[194:195]
	global_load_dwordx4 v[210:213], v[128:129], off offset:2048 nt
	global_load_dwordx4 v[218:221], v[128:129], off offset:2304 nt
	v_lshl_add_u64 v[130:131], v[132:133], 0, v[194:195]
	global_load_dwordx4 v[214:217], v[130:131], off nt
	global_load_dwordx4 v[222:225], v[130:131], off offset:256 nt
	v_or_b32_e32 v132, 16, v196
	v_mov_b32_e32 v133, v197
	v_or_b32_e32 v134, 32, v196
	v_mov_b32_e32 v135, v197
	v_or_b32_e32 v136, 48, v196
	v_mov_b32_e32 v137, v197
	v_lshlrev_b64 v[138:139], 12, v[132:133]
	v_lshlrev_b64 v[202:203], 11, v[132:133]
	v_lshlrev_b64 v[132:133], 12, v[134:135]
	v_lshlrev_b64 v[200:201], 11, v[134:135]
	v_lshlrev_b64 v[134:135], 12, v[136:137]
	v_lshlrev_b64 v[198:199], 11, v[136:137]
	v_lshl_add_u64 v[136:137], s[14:15], 0, v[138:139]
	v_lshl_add_u64 v[138:139], s[6:7], 0, v[202:203]
	v_lshl_add_u64 v[132:133], s[14:15], 0, v[132:133]
	v_lshl_add_u64 v[140:141], s[6:7], 0, v[200:201]
	v_lshl_add_u64 v[128:129], s[14:15], 0, v[134:135]
	v_lshl_add_u64 v[134:135], s[6:7], 0, v[198:199]
	v_lshl_add_u64 v[130:131], v[136:137], 0, v[194:195]
	v_lshl_add_u64 v[136:137], v[138:139], 0, v[194:195]
	v_lshl_add_u64 v[132:133], v[132:133], 0, v[194:195]
	v_lshl_add_u64 v[138:139], v[140:141], 0, v[194:195]
	v_lshl_add_u64 v[128:129], v[128:129], 0, v[194:195]
	v_lshl_add_u64 v[228:229], v[134:135], 0, v[194:195]
	global_load_dwordx4 v[172:175], v[130:131], off offset:2048 nt
	global_load_dwordx4 v[164:167], v[130:131], off offset:2304 nt
	global_load_dwordx4 v[168:171], v[136:137], off nt
	global_load_dwordx4 v[160:163], v[136:137], off offset:256 nt
	global_load_dwordx4 v[156:159], v[132:133], off offset:2048 nt
	global_load_dwordx4 v[148:151], v[132:133], off offset:2304 nt
	global_load_dwordx4 v[152:155], v[138:139], off nt
	global_load_dwordx4 v[144:147], v[138:139], off offset:256 nt
	global_load_dwordx4 v[140:143], v[128:129], off offset:2048 nt
	s_nop 0
	global_load_dwordx4 v[132:135], v[128:129], off offset:2304 nt
	global_load_dwordx4 v[136:139], v[228:229], off nt
	s_nop 0
	global_load_dwordx4 v[128:131], v[228:229], off offset:256 nt
	s_andn2_b64 vcc, exec, s[2:3]
	s_mov_b64 s[2:3], -1
	s_waitcnt vmcnt(0)
	v_lshlrev_b32_e32 v209, 16, v210
	v_and_b32_e32 v230, 0xffff0000, v210
	v_lshlrev_b32_e32 v231, 16, v211
	v_and_b32_e32 v232, 0xffff0000, v211
	v_lshlrev_b32_e32 v228, 16, v214
	v_and_b32_e32 v229, 0xffff0000, v214
	v_lshlrev_b32_e32 v210, 16, v215
	v_and_b32_e32 v211, 0xffff0000, v215
	v_lshlrev_b32_e32 v233, 16, v212
	v_and_b32_e32 v212, 0xffff0000, v212
	v_lshlrev_b32_e32 v214, 16, v216
	v_and_b32_e32 v215, 0xffff0000, v216
	v_lshlrev_b32_e32 v216, 16, v213
	v_and_b32_e32 v213, 0xffff0000, v213
	v_mul_f32_e32 v209, 0xbfb8aa3b, v209
	v_mul_f32_e32 v230, 0xbfb8aa3b, v230
	v_mul_f32_e32 v231, 0xbfb8aa3b, v231
	v_mul_f32_e32 v232, 0xbfb8aa3b, v232
	v_mul_f32_e32 v212, 0xbfb8aa3b, v212
	v_mul_f32_e32 v234, 0xbfb8aa3b, v213
	v_exp_f32_e32 v209, v209
	v_exp_f32_e32 v213, v230
	v_exp_f32_e32 v230, v231
	v_exp_f32_e32 v231, v232
	v_exp_f32_e32 v212, v212
	v_mul_f32_e32 v233, 0xbfb8aa3b, v233
	v_add_f32_e32 v209, 1.0, v209
	v_add_f32_e32 v213, 1.0, v213
	v_add_f32_e32 v230, 1.0, v230
	v_add_f32_e32 v231, 1.0, v231
	v_mul_f32_e32 v216, 0xbfb8aa3b, v216
	v_exp_f32_e32 v232, v233
	v_add_f32_e32 v233, 1.0, v212
	v_rcp_f32_e32 v212, v209
	v_rcp_f32_e32 v213, v213
	v_rcp_f32_e32 v230, v230
	v_rcp_f32_e32 v231, v231
	v_exp_f32_e32 v216, v216
	v_exp_f32_e32 v209, v234
	v_add_f32_e32 v232, 1.0, v232
	v_pk_fma_f32 v[124:125], v[124:125], v[212:213], v[228:229]
	v_pk_fma_f32 v[126:127], v[126:127], v[230:231], v[210:211]
	v_rcp_f32_e32 v232, v232
	v_rcp_f32_e32 v233, v233
	v_cvt_pk_bf16_f32 v124, v124, v125
	v_cvt_pk_bf16_f32 v125, v126, v127
	v_add_f32_e32 v126, 1.0, v216
	v_rcp_f32_e32 v210, v126
	v_add_f32_e32 v126, 1.0, v209
	v_rcp_f32_e32 v211, v126
	v_pk_fma_f32 v[120:121], v[120:121], v[232:233], v[214:215]
	s_nop 0
	v_cvt_pk_bf16_f32 v126, v120, v121
	v_lshlrev_b32_e32 v120, 16, v217
	v_and_b32_e32 v121, 0xffff0000, v217
	v_pk_fma_f32 v[120:121], v[122:123], v[210:211], v[120:121]
	v_lshlrev_b32_e32 v122, 16, v218
	v_and_b32_e32 v123, 0xffff0000, v218
	v_mul_f32_e32 v122, 0xbfb8aa3b, v122
	v_mul_f32_e32 v123, 0xbfb8aa3b, v123
	v_exp_f32_e32 v122, v122
	v_exp_f32_e32 v123, v123
	v_cvt_pk_bf16_f32 v127, v120, v121
	v_lshl_add_u64 v[120:121], s[10:11], 0, v[226:227]
	v_lshl_add_u64 v[120:121], v[120:121], 0, v[194:195]
	global_store_dwordx4 v[120:121], v[124:127], off
	v_add_f32_e32 v122, 1.0, v122
	v_add_f32_e32 v123, 1.0, v123
	v_lshlrev_b32_e32 v126, 16, v219
	v_and_b32_e32 v127, 0xffff0000, v219
	v_mul_f32_e32 v126, 0xbfb8aa3b, v126
	v_mul_f32_e32 v127, 0xbfb8aa3b, v127
	v_rcp_f32_e32 v122, v122
	v_rcp_f32_e32 v123, v123
	v_exp_f32_e32 v126, v126
	v_exp_f32_e32 v127, v127
	v_lshlrev_b32_e32 v124, 16, v222
	v_and_b32_e32 v125, 0xffff0000, v222
	v_pk_fma_f32 v[116:117], v[116:117], v[122:123], v[124:125]
	v_add_f32_e32 v122, 1.0, v126
	v_add_f32_e32 v123, 1.0, v127
	v_rcp_f32_e32 v122, v122
	v_rcp_f32_e32 v123, v123
	v_cvt_pk_bf16_f32 v116, v116, v117
	v_lshlrev_b32_e32 v117, 16, v220
	v_lshlrev_b32_e32 v124, 16, v223
	v_and_b32_e32 v125, 0xffff0000, v223
; __device__ __forceinline__ float bf2f(short s) { return __uint_as_float(((unsigned)(unsigned short)s) << 16); }
; __device__ __forceinline__ float bf2f(u16 u) { return __uint_as_float((unsigned)u << 16); }
; __device__ __forceinline__ unsigned pk2(float lo, float hi) { f32x2_t v = {lo, hi}; bf16x2_t b = __builtin_convertvector(v, bf16x2_t); return __builtin_bit_cast(unsigned, b); }
; __device__ __forceinline__ float sigmoidf_(float x) { return __builtin_amdgcn_rcpf(1.f + __expf(-x)); }
;     __device__ __forceinline__ void operator()(const pg8::f32x4 (&acc)[2][2][4][2], const pg8::Unit& u, int wr, int wc, int fr, int fq) const {
;     ...
;             for (int m = 0; m < 4; ++m) { const size_t row = (size_t)u.pm * 256 + ai * 128 + wr * 64 + m * 16 + fr;
; #pragma unroll
;                 for (int bj = 0; bj < 2; ++bj) { const int col = col0 + bj * 128;
;                     const pg8::f32x4 v0 = acc[ai][bj][m][0], v1 = acc[ai][bj][m][1];
;                     const float r[8] = {v0[0], v0[1], v0[2], v0[3], v1[0], v1[1], v1[2], v1[3]};
;                     const unsigned gws[4] = {gwv[m][bj].x, gwv[m][bj].y, gwv[m][bj].z, gwv[m][bj].w};
;                     const unsigned tws[4] = {twv[m][bj].x, twv[m][bj].y, twv[m][bj].z, twv[m][bj].w};
;                     unsigned ow[4];
; #pragma unroll
;                     for (int e = 0; e < 4; ++e) {
;                         float a0 = sigmoidf_(bf2f((u16)(gws[e] & 0xffffu))) * r[2 * e], a1 = sigmoidf_(bf2f((u16)(gws[e] >> 16))) * r[2 * e + 1];
;                         if (MODE == 1) { a0 += bf2f((u16)(tws[e] & 0xffffu)); a1 += bf2f((u16)(tws[e] >> 16)); }
;                         ow[e] = pk2(a0, a1); }
;                     v4u w = {ow[0], ow[1], ow[2], ow[3]};
;                     *(v4u*)((MODE == 0 ? T1 : MRG) + row * 1024 + col) = w; } }
	v_mul_f32_e32 v117, 0xbfb8aa3b, v117
	v_pk_fma_f32 v[118:119], v[118:119], v[122:123], v[124:125]
	v_exp_f32_e32 v122, v117
	v_and_b32_e32 v117, 0xffff0000, v220
	v_mul_f32_e32 v117, 0xbfb8aa3b, v117
	v_exp_f32_e32 v123, v117
	v_lshlrev_b32_e32 v124, 16, v221
	v_cvt_pk_bf16_f32 v117, v118, v119
	v_add_f32_e32 v118, 1.0, v122
	v_add_f32_e32 v119, 1.0, v123
	v_mul_f32_e32 v124, 0xbfb8aa3b, v124
	v_and_b32_e32 v125, 0xffff0000, v221
	v_rcp_f32_e32 v118, v118
	v_rcp_f32_e32 v119, v119
	v_exp_f32_e32 v124, v124
	v_mul_f32_e32 v125, 0xbfb8aa3b, v125
	v_exp_f32_e32 v125, v125
	v_lshlrev_b32_e32 v122, 16, v224
	v_and_b32_e32 v123, 0xffff0000, v224
	v_pk_fma_f32 v[112:113], v[112:113], v[118:119], v[122:123]
	v_add_f32_e32 v118, 1.0, v124
	v_rcp_f32_e32 v122, v118
	v_add_f32_e32 v118, 1.0, v125
	v_rcp_f32_e32 v123, v118
	v_cvt_pk_bf16_f32 v118, v112, v113
	v_lshlrev_b32_e32 v112, 16, v225
	v_and_b32_e32 v113, 0xffff0000, v225
	v_pk_fma_f32 v[112:113], v[114:115], v[122:123], v[112:113]
	v_lshlrev_b32_e32 v114, 16, v168
	v_cvt_pk_bf16_f32 v119, v112, v113
	v_lshlrev_b32_e32 v112, 16, v172
	v_and_b32_e32 v113, 0xffff0000, v172
	v_mul_f32_e32 v112, 0xbfb8aa3b, v112
	v_mul_f32_e32 v113, 0xbfb8aa3b, v113
	v_exp_f32_e32 v112, v112
	v_exp_f32_e32 v113, v113
	global_store_dwordx4 v[120:121], v[116:119], off offset:256
	v_and_b32_e32 v115, 0xffff0000, v168
	v_add_f32_e32 v112, 1.0, v112
	v_lshlrev_b32_e32 v116, 16, v173
	v_and_b32_e32 v117, 0xffff0000, v173
	v_add_f32_e32 v113, 1.0, v113
	v_mul_f32_e32 v116, 0xbfb8aa3b, v116
	v_mul_f32_e32 v117, 0xbfb8aa3b, v117
	v_rcp_f32_e32 v112, v112
	v_rcp_f32_e32 v113, v113
	v_exp_f32_e32 v116, v116
	v_exp_f32_e32 v117, v117
	v_pk_fma_f32 v[108:109], v[108:109], v[112:113], v[114:115]
	v_add_f32_e32 v112, 1.0, v116
	v_add_f32_e32 v113, 1.0, v117
	v_rcp_f32_e32 v112, v112
	v_rcp_f32_e32 v113, v113
	v_cvt_pk_bf16_f32 v108, v108, v109
	v_lshlrev_b32_e32 v109, 16, v174
	v_lshlrev_b32_e32 v114, 16, v169
	v_and_b32_e32 v115, 0xffff0000, v169
	v_mul_f32_e32 v109, 0xbfb8aa3b, v109
	v_pk_fma_f32 v[110:111], v[110:111], v[112:113], v[114:115]
	v_exp_f32_e32 v112, v109
	v_and_b32_e32 v109, 0xffff0000, v174
	v_mul_f32_e32 v109, 0xbfb8aa3b, v109
	v_exp_f32_e32 v113, v109
	v_lshlrev_b32_e32 v114, 16, v175
	v_cvt_pk_bf16_f32 v109, v110, v111
	v_add_f32_e32 v110, 1.0, v112
	v_add_f32_e32 v111, 1.0, v113
	v_mul_f32_e32 v114, 0xbfb8aa3b, v114
	v_and_b32_e32 v115, 0xffff0000, v175
	v_rcp_f32_e32 v110, v110
	v_rcp_f32_e32 v111, v111
	v_exp_f32_e32 v114, v114
	v_mul_f32_e32 v115, 0xbfb8aa3b, v115
	v_exp_f32_e32 v115, v115
	v_lshlrev_b32_e32 v112, 16, v170
	v_and_b32_e32 v113, 0xffff0000, v170
	v_pk_fma_f32 v[104:105], v[104:105], v[110:111], v[112:113]
	v_add_f32_e32 v110, 1.0, v114
	v_rcp_f32_e32 v112, v110
	v_add_f32_e32 v110, 1.0, v115
	v_rcp_f32_e32 v113, v110
	v_cvt_pk_bf16_f32 v110, v104, v105
	v_lshlrev_b32_e32 v104, 16, v171
	v_and_b32_e32 v105, 0xffff0000, v171
	v_pk_fma_f32 v[104:105], v[106:107], v[112:113], v[104:105]
	v_lshlrev_b32_e32 v106, 16, v164
	v_and_b32_e32 v107, 0xffff0000, v164
	v_mul_f32_e32 v106, 0xbfb8aa3b, v106
	v_mul_f32_e32 v107, 0xbfb8aa3b, v107
	v_exp_f32_e32 v106, v106
	v_exp_f32_e32 v107, v107
	v_cvt_pk_bf16_f32 v111, v104, v105
	v_lshl_add_u64 v[104:105], s[10:11], 0, v[202:203]
	v_lshl_add_u64 v[104:105], v[104:105], 0, v[194:195]
	global_store_dwordx4 v[104:105], v[108:111], off
	v_add_f32_e32 v106, 1.0, v106
	v_add_f32_e32 v107, 1.0, v107
	v_lshlrev_b32_e32 v110, 16, v165
	v_and_b32_e32 v111, 0xffff0000, v165
	v_mul_f32_e32 v110, 0xbfb8aa3b, v110
	v_mul_f32_e32 v111, 0xbfb8aa3b, v111
	v_rcp_f32_e32 v106, v106
	v_rcp_f32_e32 v107, v107
	v_exp_f32_e32 v110, v110
	v_exp_f32_e32 v111, v111
	v_lshlrev_b32_e32 v108, 16, v160
	v_and_b32_e32 v109, 0xffff0000, v160
	v_pk_fma_f32 v[100:101], v[100:101], v[106:107], v[108:109]
	v_add_f32_e32 v106, 1.0, v110
	v_add_f32_e32 v107, 1.0, v111
	v_rcp_f32_e32 v106, v106
	v_rcp_f32_e32 v107, v107
	v_cvt_pk_bf16_f32 v100, v100, v101
	v_lshlrev_b32_e32 v101, 16, v166
	v_lshlrev_b32_e32 v108, 16, v161
	v_and_b32_e32 v109, 0xffff0000, v161
	v_mul_f32_e32 v101, 0xbfb8aa3b, v101
	v_pk_fma_f32 v[102:103], v[102:103], v[106:107], v[108:109]
	v_exp_f32_e32 v106, v101
	v_and_b32_e32 v101, 0xffff0000, v166
	v_mul_f32_e32 v101, 0xbfb8aa3b, v101
	v_exp_f32_e32 v107, v101
	v_lshlrev_b32_e32 v108, 16, v167
	v_cvt_pk_bf16_f32 v101, v102, v103
	v_add_f32_e32 v102, 1.0, v106
	v_add_f32_e32 v103, 1.0, v107
	v_mul_f32_e32 v108, 0xbfb8aa3b, v108
	v_and_b32_e32 v109, 0xffff0000, v167
	v_rcp_f32_e32 v102, v102
	v_rcp_f32_e32 v103, v103
	v_exp_f32_e32 v108, v108
	v_mul_f32_e32 v109, 0xbfb8aa3b, v109
	v_exp_f32_e32 v109, v109
	v_lshlrev_b32_e32 v106, 16, v162
	v_and_b32_e32 v107, 0xffff0000, v162
	v_pk_fma_f32 v[96:97], v[96:97], v[102:103], v[106:107]
	v_add_f32_e32 v102, 1.0, v108
	v_rcp_f32_e32 v106, v102
	v_add_f32_e32 v102, 1.0, v109
	v_rcp_f32_e32 v107, v102
	v_cvt_pk_bf16_f32 v102, v96, v97
	v_lshlrev_b32_e32 v96, 16, v163
	v_and_b32_e32 v97, 0xffff0000, v163
	v_pk_fma_f32 v[96:97], v[98:99], v[106:107], v[96:97]
	v_lshlrev_b32_e32 v98, 16, v152
	v_cvt_pk_bf16_f32 v103, v96, v97
	v_lshlrev_b32_e32 v96, 16, v156
	v_and_b32_e32 v97, 0xffff0000, v156
	v_mul_f32_e32 v96, 0xbfb8aa3b, v96
	v_mul_f32_e32 v97, 0xbfb8aa3b, v97
	v_exp_f32_e32 v96, v96
	v_exp_f32_e32 v97, v97
	global_store_dwordx4 v[104:105], v[100:103], off offset:256
	v_and_b32_e32 v99, 0xffff0000, v152
	v_add_f32_e32 v96, 1.0, v96
	v_lshlrev_b32_e32 v100, 16, v157
	v_and_b32_e32 v101, 0xffff0000, v157
	v_add_f32_e32 v97, 1.0, v97
	v_mul_f32_e32 v100, 0xbfb8aa3b, v100
	v_mul_f32_e32 v101, 0xbfb8aa3b, v101
	v_rcp_f32_e32 v96, v96
; __device__ __forceinline__ float bf2f(short s) { return __uint_as_float(((unsigned)(unsigned short)s) << 16); }
; __device__ __forceinline__ float bf2f(u16 u) { return __uint_as_float((unsigned)u << 16); }
; __device__ __forceinline__ unsigned pk2(float lo, float hi) { f32x2_t v = {lo, hi}; bf16x2_t b = __builtin_convertvector(v, bf16x2_t); return __builtin_bit_cast(unsigned, b); }
; __device__ __forceinline__ float sigmoidf_(float x) { return __builtin_amdgcn_rcpf(1.f + __expf(-x)); }
;     __device__ __forceinline__ void operator()(const pg8::f32x4 (&acc)[2][2][4][2], const pg8::Unit& u, int wr, int wc, int fr, int fq) const {
;     ...
;             for (int m = 0; m < 4; ++m) { const size_t row = (size_t)u.pm * 256 + ai * 128 + wr * 64 + m * 16 + fr;
; #pragma unroll
;                 for (int bj = 0; bj < 2; ++bj) { const int col = col0 + bj * 128;
;                     const pg8::f32x4 v0 = acc[ai][bj][m][0], v1 = acc[ai][bj][m][1];
;                     const float r[8] = {v0[0], v0[1], v0[2], v0[3], v1[0], v1[1], v1[2], v1[3]};
;                     const unsigned gws[4] = {gwv[m][bj].x, gwv[m][bj].y, gwv[m][bj].z, gwv[m][bj].w};
;                     const unsigned tws[4] = {twv[m][bj].x, twv[m][bj].y, twv[m][bj].z, twv[m][bj].w};
;                     unsigned ow[4];
; #pragma unroll
;                     for (int e = 0; e < 4; ++e) {
;                         float a0 = sigmoidf_(bf2f((u16)(gws[e] & 0xffffu))) * r[2 * e], a1 = sigmoidf_(bf2f((u16)(gws[e] >> 16))) * r[2 * e + 1];
;                         if (MODE == 1) { a0 += bf2f((u16)(tws[e] & 0xffffu)); a1 += bf2f((u16)(tws[e] >> 16)); }
;                         ow[e] = pk2(a0, a1); }
;                     v4u w = {ow[0], ow[1], ow[2], ow[3]};
;                     *(v4u*)((MODE == 0 ? T1 : MRG) + row * 1024 + col) = w; } }
	v_rcp_f32_e32 v97, v97
	v_exp_f32_e32 v100, v100
	v_exp_f32_e32 v101, v101
	v_pk_fma_f32 v[92:93], v[92:93], v[96:97], v[98:99]
	v_add_f32_e32 v96, 1.0, v100
	v_add_f32_e32 v97, 1.0, v101
	v_rcp_f32_e32 v96, v96
	v_rcp_f32_e32 v97, v97
	v_cvt_pk_bf16_f32 v92, v92, v93
	v_lshlrev_b32_e32 v93, 16, v158
	v_lshlrev_b32_e32 v98, 16, v153
	v_and_b32_e32 v99, 0xffff0000, v153
	v_mul_f32_e32 v93, 0xbfb8aa3b, v93
	v_pk_fma_f32 v[94:95], v[94:95], v[96:97], v[98:99]
	v_exp_f32_e32 v96, v93
	v_and_b32_e32 v93, 0xffff0000, v158
	v_mul_f32_e32 v93, 0xbfb8aa3b, v93
	v_exp_f32_e32 v97, v93
	v_lshlrev_b32_e32 v98, 16, v159
	v_cvt_pk_bf16_f32 v93, v94, v95
	v_add_f32_e32 v94, 1.0, v96
	v_add_f32_e32 v95, 1.0, v97
	v_mul_f32_e32 v98, 0xbfb8aa3b, v98
	v_and_b32_e32 v99, 0xffff0000, v159
	v_rcp_f32_e32 v94, v94
	v_rcp_f32_e32 v95, v95
	v_exp_f32_e32 v98, v98
	v_mul_f32_e32 v99, 0xbfb8aa3b, v99
	v_exp_f32_e32 v99, v99
	v_lshlrev_b32_e32 v96, 16, v154
	v_and_b32_e32 v97, 0xffff0000, v154
	v_pk_fma_f32 v[88:89], v[88:89], v[94:95], v[96:97]
	v_add_f32_e32 v94, 1.0, v98
	v_rcp_f32_e32 v96, v94
	v_add_f32_e32 v94, 1.0, v99
	v_rcp_f32_e32 v97, v94
	v_cvt_pk_bf16_f32 v94, v88, v89
	v_lshlrev_b32_e32 v88, 16, v155
	v_and_b32_e32 v89, 0xffff0000, v155
	v_pk_fma_f32 v[88:89], v[90:91], v[96:97], v[88:89]
	v_lshlrev_b32_e32 v90, 16, v148
	v_and_b32_e32 v91, 0xffff0000, v148
	v_mul_f32_e32 v90, 0xbfb8aa3b, v90
	v_mul_f32_e32 v91, 0xbfb8aa3b, v91
	v_exp_f32_e32 v90, v90
	v_exp_f32_e32 v91, v91
	v_cvt_pk_bf16_f32 v95, v88, v89
	v_lshl_add_u64 v[88:89], s[10:11], 0, v[200:201]
	v_lshl_add_u64 v[88:89], v[88:89], 0, v[194:195]
	global_store_dwordx4 v[88:89], v[92:95], off
	v_add_f32_e32 v90, 1.0, v90
	v_add_f32_e32 v91, 1.0, v91
	v_lshlrev_b32_e32 v94, 16, v149
	v_and_b32_e32 v95, 0xffff0000, v149
	v_mul_f32_e32 v94, 0xbfb8aa3b, v94
	v_mul_f32_e32 v95, 0xbfb8aa3b, v95
	v_rcp_f32_e32 v90, v90
	v_rcp_f32_e32 v91, v91
	v_exp_f32_e32 v94, v94
	v_exp_f32_e32 v95, v95
	v_lshlrev_b32_e32 v92, 16, v144
	v_and_b32_e32 v93, 0xffff0000, v144
	v_pk_fma_f32 v[84:85], v[84:85], v[90:91], v[92:93]
	v_add_f32_e32 v90, 1.0, v94
	v_add_f32_e32 v91, 1.0, v95
	v_rcp_f32_e32 v90, v90
	v_rcp_f32_e32 v91, v91
	v_cvt_pk_bf16_f32 v84, v84, v85
	v_lshlrev_b32_e32 v85, 16, v150
	v_lshlrev_b32_e32 v92, 16, v145
	v_and_b32_e32 v93, 0xffff0000, v145
	v_mul_f32_e32 v85, 0xbfb8aa3b, v85
	v_pk_fma_f32 v[86:87], v[86:87], v[90:91], v[92:93]
	v_exp_f32_e32 v90, v85
	v_and_b32_e32 v85, 0xffff0000, v150
	v_mul_f32_e32 v85, 0xbfb8aa3b, v85
	v_exp_f32_e32 v91, v85
	v_lshlrev_b32_e32 v92, 16, v151
	v_cvt_pk_bf16_f32 v85, v86, v87
	v_add_f32_e32 v86, 1.0, v90
	v_add_f32_e32 v87, 1.0, v91
	v_mul_f32_e32 v92, 0xbfb8aa3b, v92
	v_and_b32_e32 v93, 0xffff0000, v151
	v_rcp_f32_e32 v86, v86
	v_rcp_f32_e32 v87, v87
	v_exp_f32_e32 v92, v92
	v_mul_f32_e32 v93, 0xbfb8aa3b, v93
	v_exp_f32_e32 v93, v93
	v_lshlrev_b32_e32 v90, 16, v146
	v_and_b32_e32 v91, 0xffff0000, v146
	v_pk_fma_f32 v[80:81], v[80:81], v[86:87], v[90:91]
	v_add_f32_e32 v86, 1.0, v92
	v_rcp_f32_e32 v90, v86
	v_add_f32_e32 v86, 1.0, v93
	v_rcp_f32_e32 v91, v86
	v_cvt_pk_bf16_f32 v86, v80, v81
	v_lshlrev_b32_e32 v80, 16, v147
	v_and_b32_e32 v81, 0xffff0000, v147
	v_pk_fma_f32 v[80:81], v[82:83], v[90:91], v[80:81]
	v_lshlrev_b32_e32 v82, 16, v136
	v_cvt_pk_bf16_f32 v87, v80, v81
	v_lshlrev_b32_e32 v80, 16, v140
	v_and_b32_e32 v81, 0xffff0000, v140
	v_mul_f32_e32 v80, 0xbfb8aa3b, v80
	v_mul_f32_e32 v81, 0xbfb8aa3b, v81
	v_exp_f32_e32 v80, v80
	v_exp_f32_e32 v81, v81
	global_store_dwordx4 v[88:89], v[84:87], off offset:256
	v_and_b32_e32 v83, 0xffff0000, v136
	v_add_f32_e32 v80, 1.0, v80
	v_lshlrev_b32_e32 v84, 16, v141
	v_and_b32_e32 v85, 0xffff0000, v141
	v_add_f32_e32 v81, 1.0, v81
	v_mul_f32_e32 v84, 0xbfb8aa3b, v84
	v_mul_f32_e32 v85, 0xbfb8aa3b, v85
	v_rcp_f32_e32 v80, v80
	v_rcp_f32_e32 v81, v81
	v_exp_f32_e32 v84, v84
	v_exp_f32_e32 v85, v85
	v_pk_fma_f32 v[76:77], v[76:77], v[80:81], v[82:83]
	v_add_f32_e32 v80, 1.0, v84
	v_add_f32_e32 v81, 1.0, v85
	v_rcp_f32_e32 v80, v80
	v_rcp_f32_e32 v81, v81
	v_cvt_pk_bf16_f32 v76, v76, v77
	v_lshlrev_b32_e32 v77, 16, v142
	v_lshlrev_b32_e32 v82, 16, v137
	v_and_b32_e32 v83, 0xffff0000, v137
	v_mul_f32_e32 v77, 0xbfb8aa3b, v77
	v_pk_fma_f32 v[78:79], v[78:79], v[80:81], v[82:83]
	v_exp_f32_e32 v80, v77
	v_and_b32_e32 v77, 0xffff0000, v142
	v_mul_f32_e32 v77, 0xbfb8aa3b, v77
	v_exp_f32_e32 v81, v77
	v_lshlrev_b32_e32 v82, 16, v143
	v_cvt_pk_bf16_f32 v77, v78, v79
	v_add_f32_e32 v78, 1.0, v80
	v_add_f32_e32 v79, 1.0, v81
	v_mul_f32_e32 v82, 0xbfb8aa3b, v82
	v_and_b32_e32 v83, 0xffff0000, v143
	v_rcp_f32_e32 v78, v78
	v_rcp_f32_e32 v79, v79
	v_exp_f32_e32 v82, v82
	v_mul_f32_e32 v83, 0xbfb8aa3b, v83
	v_exp_f32_e32 v83, v83
	v_lshlrev_b32_e32 v80, 16, v138
	v_and_b32_e32 v81, 0xffff0000, v138
	v_pk_fma_f32 v[72:73], v[72:73], v[78:79], v[80:81]
	v_add_f32_e32 v78, 1.0, v82
	v_rcp_f32_e32 v80, v78
	v_add_f32_e32 v78, 1.0, v83
	v_rcp_f32_e32 v81, v78
	v_cvt_pk_bf16_f32 v78, v72, v73
	v_lshlrev_b32_e32 v72, 16, v139
	v_and_b32_e32 v73, 0xffff0000, v139
	v_pk_fma_f32 v[72:73], v[74:75], v[80:81], v[72:73]
	v_lshlrev_b32_e32 v74, 16, v132
	v_and_b32_e32 v75, 0xffff0000, v132
	v_mul_f32_e32 v74, 0xbfb8aa3b, v74
	v_mul_f32_e32 v75, 0xbfb8aa3b, v75
	v_exp_f32_e32 v74, v74
	v_exp_f32_e32 v75, v75
	v_cvt_pk_bf16_f32 v79, v72, v73
	v_lshl_add_u64 v[72:73], s[10:11], 0, v[198:199]
	v_lshl_add_u64 v[72:73], v[72:73], 0, v[194:195]
	global_store_dwordx4 v[72:73], v[76:79], off
	v_add_f32_e32 v74, 1.0, v74
	v_add_f32_e32 v75, 1.0, v75
	v_lshlrev_b32_e32 v78, 16, v133
	v_and_b32_e32 v79, 0xffff0000, v133
	v_mul_f32_e32 v78, 0xbfb8aa3b, v78
; __device__ __forceinline__ float bf2f(short s) { return __uint_as_float(((unsigned)(unsigned short)s) << 16); }
; __device__ __forceinline__ float bf2f(u16 u) { return __uint_as_float((unsigned)u << 16); }
; __device__ __forceinline__ unsigned pk2(float lo, float hi) { f32x2_t v = {lo, hi}; bf16x2_t b = __builtin_convertvector(v, bf16x2_t); return __builtin_bit_cast(unsigned, b); }
;     __device__ __forceinline__ void operator()(const pg8::f32x4 (&acc)[2][2][4][2], const pg8::Unit& u, int wr, int wc, int fr, int fq) const {
;     ...
;         for (int ai = 0; ai < 2; ++ai) {
;             v4u gwv[4][2], twv[4][2];
; #pragma unroll
;             for (int m = 0; m < 4; ++m) { const size_t row = (size_t)u.pm * 256 + ai * 128 + wr * 64 + m * 16 + fr;
; #pragma unroll
;                 for (int bj = 0; bj < 2; ++bj) { const int col = col0 + bj * 128;
;                     gwv[m][bj] = __builtin_nontemporal_load((const v4u*)(MG + row * 2048 + MODE * 1024 + col));
;                     twv[m][bj] = (MODE == 1) ? __builtin_nontemporal_load((const v4u*)(T1 + row * 1024 + col)) : (v4u){0u, 0u, 0u, 0u}; } }
; #pragma unroll
;             for (int m = 0; m < 4; ++m) { const size_t row = (size_t)u.pm * 256 + ai * 128 + wr * 64 + m * 16 + fr;
; #pragma unroll
;                 for (int bj = 0; bj < 2; ++bj) { const int col = col0 + bj * 128;
;                     const pg8::f32x4 v0 = acc[ai][bj][m][0], v1 = acc[ai][bj][m][1];
;                     const float r[8] = {v0[0], v0[1], v0[2], v0[3], v1[0], v1[1], v1[2], v1[3]};
;                     const unsigned gws[4] = {gwv[m][bj].x, gwv[m][bj].y, gwv[m][bj].z, gwv[m][bj].w};
;                     const unsigned tws[4] = {twv[m][bj].x, twv[m][bj].y, twv[m][bj].z, twv[m][bj].w};
;                     unsigned ow[4];
; #pragma unroll
;                     for (int e = 0; e < 4; ++e) {
;                         float a0 = sigmoidf_(bf2f((u16)(gws[e] & 0xffffu))) * r[2 * e], a1 = sigmoidf_(bf2f((u16)(gws[e] >> 16))) * r[2 * e + 1];
;                         if (MODE == 1) { a0 += bf2f((u16)(tws[e] & 0xffffu)); a1 += bf2f((u16)(tws[e] >> 16)); }
;                         ow[e] = pk2(a0, a1); }
;                     v4u w = {ow[0], ow[1], ow[2], ow[3]};
;                     *(v4u*)((MODE == 0 ? T1 : MRG) + row * 1024 + col) = w; } }
	v_mul_f32_e32 v79, 0xbfb8aa3b, v79
	v_rcp_f32_e32 v74, v74
	v_rcp_f32_e32 v75, v75
	v_exp_f32_e32 v78, v78
	v_exp_f32_e32 v79, v79
	v_lshlrev_b32_e32 v76, 16, v128
	v_and_b32_e32 v77, 0xffff0000, v128
	v_pk_fma_f32 v[68:69], v[68:69], v[74:75], v[76:77]
	v_add_f32_e32 v74, 1.0, v78
	v_add_f32_e32 v75, 1.0, v79
	v_rcp_f32_e32 v74, v74
	v_rcp_f32_e32 v75, v75
	v_cvt_pk_bf16_f32 v68, v68, v69
	v_lshlrev_b32_e32 v69, 16, v134
	v_lshlrev_b32_e32 v76, 16, v129
	v_and_b32_e32 v77, 0xffff0000, v129
	v_mul_f32_e32 v69, 0xbfb8aa3b, v69
	v_pk_fma_f32 v[70:71], v[70:71], v[74:75], v[76:77]
	v_exp_f32_e32 v74, v69
	v_and_b32_e32 v69, 0xffff0000, v134
	v_mul_f32_e32 v69, 0xbfb8aa3b, v69
	v_exp_f32_e32 v75, v69
	v_lshlrev_b32_e32 v76, 16, v135
	v_cvt_pk_bf16_f32 v69, v70, v71
	v_add_f32_e32 v70, 1.0, v74
	v_add_f32_e32 v71, 1.0, v75
	v_mul_f32_e32 v76, 0xbfb8aa3b, v76
	v_and_b32_e32 v77, 0xffff0000, v135
	v_rcp_f32_e32 v70, v70
	v_rcp_f32_e32 v71, v71
	v_exp_f32_e32 v76, v76
	v_mul_f32_e32 v77, 0xbfb8aa3b, v77
	v_exp_f32_e32 v77, v77
	v_lshlrev_b32_e32 v74, 16, v130
	v_and_b32_e32 v75, 0xffff0000, v130
	v_pk_fma_f32 v[64:65], v[64:65], v[70:71], v[74:75]
	v_add_f32_e32 v70, 1.0, v76
	v_rcp_f32_e32 v74, v70
	v_add_f32_e32 v70, 1.0, v77
	v_rcp_f32_e32 v75, v70
	v_cvt_pk_bf16_f32 v70, v64, v65
	v_lshlrev_b32_e32 v64, 16, v131
	v_and_b32_e32 v65, 0xffff0000, v131
	v_pk_fma_f32 v[64:65], v[66:67], v[74:75], v[64:65]
	s_nop 0
	v_cvt_pk_bf16_f32 v71, v64, v65
	v_lshl_add_u64 v[64:65], v[196:197], 0, s[12:13]
	v_lshlrev_b64 v[66:67], 12, v[64:65]
	v_lshl_add_u64 v[66:67], s[14:15], 0, v[66:67]
	global_store_dwordx4 v[72:73], v[68:71], off offset:256
	v_lshl_add_u64 v[66:67], v[66:67], 0, v[194:195]
	global_load_dwordx4 v[118:121], v[66:67], off offset:2048 nt
	v_lshlrev_b64 v[134:135], 11, v[64:65]
	v_lshl_add_u64 v[64:65], s[6:7], 0, v[134:135]
	v_lshl_add_u64 v[64:65], v[64:65], 0, v[194:195]
	global_load_dwordx4 v[122:125], v[64:65], off nt
	global_load_dwordx4 v[126:129], v[66:67], off offset:2304 nt
	global_load_dwordx4 v[130:133], v[64:65], off offset:256 nt
	v_lshl_add_u64 v[64:65], v[196:197], 0, s[18:19]
	v_lshlrev_b64 v[66:67], 12, v[64:65]
	v_lshlrev_b64 v[116:117], 11, v[64:65]
	v_lshl_add_u64 v[66:67], s[14:15], 0, v[66:67]
	v_lshl_add_u64 v[64:65], s[6:7], 0, v[116:117]
	v_lshl_add_u64 v[66:67], v[66:67], 0, v[194:195]
	v_lshl_add_u64 v[64:65], v[64:65], 0, v[194:195]
	global_load_dwordx4 v[108:111], v[66:67], off offset:2048 nt
	global_load_dwordx4 v[100:103], v[66:67], off offset:2304 nt
	global_load_dwordx4 v[104:107], v[64:65], off nt
	global_load_dwordx4 v[96:99], v[64:65], off offset:256 nt
	v_lshl_add_u64 v[64:65], v[196:197], 0, s[20:21]
	v_lshlrev_b64 v[66:67], 12, v[64:65]
	v_lshlrev_b64 v[114:115], 11, v[64:65]
	v_lshl_add_u64 v[66:67], s[14:15], 0, v[66:67]
	v_lshl_add_u64 v[64:65], s[6:7], 0, v[114:115]
	v_lshl_add_u64 v[66:67], v[66:67], 0, v[194:195]
	v_lshl_add_u64 v[64:65], v[64:65], 0, v[194:195]
	global_load_dwordx4 v[92:95], v[66:67], off offset:2048 nt
	global_load_dwordx4 v[84:87], v[66:67], off offset:2304 nt
	global_load_dwordx4 v[88:91], v[64:65], off nt
	global_load_dwordx4 v[80:83], v[64:65], off offset:256 nt
	v_lshl_add_u64 v[64:65], v[196:197], 0, s[22:23]
	v_lshlrev_b64 v[66:67], 12, v[64:65]
	v_lshl_add_u64 v[66:67], s[14:15], 0, v[66:67]
	v_lshl_add_u64 v[66:67], v[66:67], 0, v[194:195]
	global_load_dwordx4 v[76:79], v[66:67], off offset:2048 nt
	global_load_dwordx4 v[68:71], v[66:67], off offset:2304 nt
	v_lshlrev_b64 v[112:113], 11, v[64:65]
	v_lshl_add_u64 v[64:65], s[6:7], 0, v[112:113]
	v_lshl_add_u64 v[64:65], v[64:65], 0, v[194:195]
	s_waitcnt vmcnt(13)
	v_lshlrev_b32_e32 v66, 16, v118
	v_mul_f32_e32 v66, 0xbfb8aa3b, v66
	v_exp_f32_e32 v136, v66
	v_and_b32_e32 v66, 0xffff0000, v118
	v_mul_f32_e32 v66, 0xbfb8aa3b, v66
	v_exp_f32_e32 v118, v66
	v_add_f32_e32 v136, 1.0, v136
	v_rcp_f32_e32 v136, v136
	s_waitcnt vmcnt(12)
	v_lshlrev_b32_e32 v138, 16, v122
	v_add_f32_e32 v118, 1.0, v118
	v_rcp_f32_e32 v137, v118
	v_lshlrev_b32_e32 v118, 16, v119
	v_and_b32_e32 v119, 0xffff0000, v119
	v_mul_f32_e32 v118, 0xbfb8aa3b, v118
	v_mul_f32_e32 v119, 0xbfb8aa3b, v119
	v_exp_f32_e32 v118, v118
	v_exp_f32_e32 v119, v119
	v_and_b32_e32 v139, 0xffff0000, v122
	v_pk_fma_f32 v[60:61], v[60:61], v[136:137], v[138:139]
	v_add_f32_e32 v118, 1.0, v118
	v_add_f32_e32 v119, 1.0, v119
	v_rcp_f32_e32 v118, v118
	v_rcp_f32_e32 v119, v119
	v_cvt_pk_bf16_f32 v60, v60, v61
	v_lshlrev_b32_e32 v61, 16, v120
	v_lshlrev_b32_e32 v122, 16, v123
	v_and_b32_e32 v123, 0xffff0000, v123
	v_mul_f32_e32 v61, 0xbfb8aa3b, v61
	v_pk_fma_f32 v[62:63], v[62:63], v[118:119], v[122:123]
	v_exp_f32_e32 v118, v61
	v_and_b32_e32 v61, 0xffff0000, v120
	v_mul_f32_e32 v61, 0xbfb8aa3b, v61
	v_exp_f32_e32 v119, v61
	v_lshlrev_b32_e32 v120, 16, v121
	v_cvt_pk_bf16_f32 v61, v62, v63
	v_add_f32_e32 v62, 1.0, v118
	v_add_f32_e32 v63, 1.0, v119
	v_mul_f32_e32 v120, 0xbfb8aa3b, v120
	v_and_b32_e32 v121, 0xffff0000, v121
	v_rcp_f32_e32 v62, v62
	v_rcp_f32_e32 v63, v63
	v_exp_f32_e32 v120, v120
	v_mul_f32_e32 v121, 0xbfb8aa3b, v121
	v_exp_f32_e32 v121, v121
	v_lshlrev_b32_e32 v118, 16, v124
	v_and_b32_e32 v119, 0xffff0000, v124
	v_pk_fma_f32 v[56:57], v[56:57], v[62:63], v[118:119]
	v_add_f32_e32 v62, 1.0, v120
	v_rcp_f32_e32 v118, v62
	v_add_f32_e32 v62, 1.0, v121
	v_rcp_f32_e32 v119, v62
	v_cvt_pk_bf16_f32 v62, v56, v57
	v_lshlrev_b32_e32 v56, 16, v125
	v_and_b32_e32 v57, 0xffff0000, v125
	v_pk_fma_f32 v[56:57], v[58:59], v[118:119], v[56:57]
	s_waitcnt vmcnt(11)
; __device__ __forceinline__ float bf2f(short s) { return __uint_as_float(((unsigned)(unsigned short)s) << 16); }
; __device__ __forceinline__ float bf2f(u16 u) { return __uint_as_float((unsigned)u << 16); }
; __device__ __forceinline__ unsigned pk2(float lo, float hi) { f32x2_t v = {lo, hi}; bf16x2_t b = __builtin_convertvector(v, bf16x2_t); return __builtin_bit_cast(unsigned, b); }
;     __device__ __forceinline__ void operator()(const pg8::f32x4 (&acc)[2][2][4][2], const pg8::Unit& u, int wr, int wc, int fr, int fq) const {
;     ...
;         for (int ai = 0; ai < 2; ++ai) {
;             v4u gwv[4][2], twv[4][2];
; #pragma unroll
;             for (int m = 0; m < 4; ++m) { const size_t row = (size_t)u.pm * 256 + ai * 128 + wr * 64 + m * 16 + fr;
; #pragma unroll
;                 for (int bj = 0; bj < 2; ++bj) { const int col = col0 + bj * 128;
;                     gwv[m][bj] = __builtin_nontemporal_load((const v4u*)(MG + row * 2048 + MODE * 1024 + col));
;                     twv[m][bj] = (MODE == 1) ? __builtin_nontemporal_load((const v4u*)(T1 + row * 1024 + col)) : (v4u){0u, 0u, 0u, 0u}; } }
; #pragma unroll
;             for (int m = 0; m < 4; ++m) { const size_t row = (size_t)u.pm * 256 + ai * 128 + wr * 64 + m * 16 + fr;
; #pragma unroll
;                 for (int bj = 0; bj < 2; ++bj) { const int col = col0 + bj * 128;
;                     const pg8::f32x4 v0 = acc[ai][bj][m][0], v1 = acc[ai][bj][m][1];
;                     const float r[8] = {v0[0], v0[1], v0[2], v0[3], v1[0], v1[1], v1[2], v1[3]};
;                     const unsigned gws[4] = {gwv[m][bj].x, gwv[m][bj].y, gwv[m][bj].z, gwv[m][bj].w};
;                     const unsigned tws[4] = {twv[m][bj].x, twv[m][bj].y, twv[m][bj].z, twv[m][bj].w};
;                     unsigned ow[4];
; #pragma unroll
;                     for (int e = 0; e < 4; ++e) {
;                         float a0 = sigmoidf_(bf2f((u16)(gws[e] & 0xffffu))) * r[2 * e], a1 = sigmoidf_(bf2f((u16)(gws[e] >> 16))) * r[2 * e + 1];
;                         if (MODE == 1) { a0 += bf2f((u16)(tws[e] & 0xffffu)); a1 += bf2f((u16)(tws[e] >> 16)); }
;                         ow[e] = pk2(a0, a1); }
;                     v4u w = {ow[0], ow[1], ow[2], ow[3]};
;                     *(v4u*)((MODE == 0 ? T1 : MRG) + row * 1024 + col) = w; } }
	v_lshlrev_b32_e32 v58, 16, v126
	v_and_b32_e32 v59, 0xffff0000, v126
	v_mul_f32_e32 v58, 0xbfb8aa3b, v58
	v_mul_f32_e32 v59, 0xbfb8aa3b, v59
	v_exp_f32_e32 v58, v58
	v_exp_f32_e32 v59, v59
	v_cvt_pk_bf16_f32 v63, v56, v57
	v_lshl_add_u64 v[56:57], s[10:11], 0, v[134:135]
	v_lshl_add_u64 v[56:57], v[56:57], 0, v[194:195]
	global_load_dwordx4 v[72:75], v[64:65], off nt
	s_nop 0
	global_load_dwordx4 v[64:67], v[64:65], off offset:256 nt
	v_add_f32_e32 v58, 1.0, v58
	global_store_dwordx4 v[56:57], v[60:63], off
	v_add_f32_e32 v59, 1.0, v59
	v_rcp_f32_e32 v58, v58
	v_lshlrev_b32_e32 v62, 16, v127
	v_and_b32_e32 v63, 0xffff0000, v127
	v_mul_f32_e32 v62, 0xbfb8aa3b, v62
	v_mul_f32_e32 v63, 0xbfb8aa3b, v63
	v_rcp_f32_e32 v59, v59
	v_exp_f32_e32 v62, v62
	v_exp_f32_e32 v63, v63
	s_waitcnt vmcnt(13)
	v_lshlrev_b32_e32 v60, 16, v130
	v_and_b32_e32 v61, 0xffff0000, v130
	v_pk_fma_f32 v[52:53], v[52:53], v[58:59], v[60:61]
	v_add_f32_e32 v58, 1.0, v62
	v_add_f32_e32 v59, 1.0, v63
	v_rcp_f32_e32 v58, v58
	v_rcp_f32_e32 v59, v59
	v_cvt_pk_bf16_f32 v52, v52, v53
	v_lshlrev_b32_e32 v53, 16, v128
	v_lshlrev_b32_e32 v60, 16, v131
	v_and_b32_e32 v61, 0xffff0000, v131
	v_mul_f32_e32 v53, 0xbfb8aa3b, v53
	v_pk_fma_f32 v[54:55], v[54:55], v[58:59], v[60:61]
	v_exp_f32_e32 v58, v53
	v_and_b32_e32 v53, 0xffff0000, v128
	v_mul_f32_e32 v53, 0xbfb8aa3b, v53
	v_exp_f32_e32 v59, v53
	v_lshlrev_b32_e32 v60, 16, v129
	v_cvt_pk_bf16_f32 v53, v54, v55
	v_add_f32_e32 v54, 1.0, v58
	v_add_f32_e32 v55, 1.0, v59
	v_mul_f32_e32 v60, 0xbfb8aa3b, v60
	v_and_b32_e32 v61, 0xffff0000, v129
	v_rcp_f32_e32 v54, v54
	v_rcp_f32_e32 v55, v55
	v_exp_f32_e32 v60, v60
	v_mul_f32_e32 v61, 0xbfb8aa3b, v61
	v_exp_f32_e32 v61, v61
	v_lshlrev_b32_e32 v58, 16, v132
	v_and_b32_e32 v59, 0xffff0000, v132
	v_pk_fma_f32 v[48:49], v[48:49], v[54:55], v[58:59]
	v_add_f32_e32 v54, 1.0, v60
	v_rcp_f32_e32 v58, v54
	v_add_f32_e32 v54, 1.0, v61
	v_rcp_f32_e32 v59, v54
	v_cvt_pk_bf16_f32 v54, v48, v49
	v_lshlrev_b32_e32 v48, 16, v133
	v_and_b32_e32 v49, 0xffff0000, v133
	v_pk_fma_f32 v[48:49], v[50:51], v[58:59], v[48:49]
	s_waitcnt vmcnt(10)
	v_lshlrev_b32_e32 v50, 16, v104
	v_cvt_pk_bf16_f32 v55, v48, v49
	v_lshlrev_b32_e32 v48, 16, v108
	v_and_b32_e32 v49, 0xffff0000, v108
	v_mul_f32_e32 v48, 0xbfb8aa3b, v48
	v_mul_f32_e32 v49, 0xbfb8aa3b, v49
	v_exp_f32_e32 v48, v48
	v_exp_f32_e32 v49, v49
	global_store_dwordx4 v[56:57], v[52:55], off offset:256
	v_and_b32_e32 v51, 0xffff0000, v104
	v_add_f32_e32 v48, 1.0, v48
	v_lshlrev_b32_e32 v52, 16, v109
	v_and_b32_e32 v53, 0xffff0000, v109
	v_add_f32_e32 v49, 1.0, v49
	v_mul_f32_e32 v52, 0xbfb8aa3b, v52
	v_mul_f32_e32 v53, 0xbfb8aa3b, v53
	v_rcp_f32_e32 v48, v48
	v_rcp_f32_e32 v49, v49
	v_exp_f32_e32 v52, v52
	v_exp_f32_e32 v53, v53
	v_pk_fma_f32 v[44:45], v[44:45], v[48:49], v[50:51]
	v_add_f32_e32 v48, 1.0, v52
	v_add_f32_e32 v49, 1.0, v53
	v_rcp_f32_e32 v48, v48
	v_rcp_f32_e32 v49, v49
	v_cvt_pk_bf16_f32 v44, v44, v45
	v_lshlrev_b32_e32 v45, 16, v110
	v_lshlrev_b32_e32 v50, 16, v105
	v_and_b32_e32 v51, 0xffff0000, v105
	v_mul_f32_e32 v45, 0xbfb8aa3b, v45
	v_pk_fma_f32 v[46:47], v[46:47], v[48:49], v[50:51]
	v_exp_f32_e32 v48, v45
	v_and_b32_e32 v45, 0xffff0000, v110
	v_mul_f32_e32 v45, 0xbfb8aa3b, v45
	v_exp_f32_e32 v49, v45
	v_lshlrev_b32_e32 v50, 16, v111
	v_cvt_pk_bf16_f32 v45, v46, v47
	v_add_f32_e32 v46, 1.0, v48
	v_add_f32_e32 v47, 1.0, v49
	v_mul_f32_e32 v50, 0xbfb8aa3b, v50
	v_and_b32_e32 v51, 0xffff0000, v111
	v_rcp_f32_e32 v46, v46
	v_rcp_f32_e32 v47, v47
	v_exp_f32_e32 v50, v50
	v_mul_f32_e32 v51, 0xbfb8aa3b, v51
	v_exp_f32_e32 v51, v51
	v_lshlrev_b32_e32 v48, 16, v106
	v_and_b32_e32 v49, 0xffff0000, v106
	v_pk_fma_f32 v[40:41], v[40:41], v[46:47], v[48:49]
	v_add_f32_e32 v46, 1.0, v50
	v_rcp_f32_e32 v48, v46
	v_add_f32_e32 v46, 1.0, v51
	v_rcp_f32_e32 v49, v46
	v_cvt_pk_bf16_f32 v46, v40, v41
	v_lshlrev_b32_e32 v40, 16, v107
	v_and_b32_e32 v41, 0xffff0000, v107
	v_pk_fma_f32 v[40:41], v[42:43], v[48:49], v[40:41]
	v_lshlrev_b32_e32 v42, 16, v100
	v_and_b32_e32 v43, 0xffff0000, v100
	v_mul_f32_e32 v42, 0xbfb8aa3b, v42
	v_mul_f32_e32 v43, 0xbfb8aa3b, v43
	v_exp_f32_e32 v42, v42
	v_exp_f32_e32 v43, v43
	v_cvt_pk_bf16_f32 v47, v40, v41
	v_lshl_add_u64 v[40:41], s[10:11], 0, v[116:117]
	v_lshl_add_u64 v[40:41], v[40:41], 0, v[194:195]
	global_store_dwordx4 v[40:41], v[44:47], off
	v_add_f32_e32 v42, 1.0, v42
	v_add_f32_e32 v43, 1.0, v43
	v_lshlrev_b32_e32 v46, 16, v101
	v_and_b32_e32 v47, 0xffff0000, v101
	v_mul_f32_e32 v46, 0xbfb8aa3b, v46
	v_mul_f32_e32 v47, 0xbfb8aa3b, v47
	v_rcp_f32_e32 v42, v42
	v_rcp_f32_e32 v43, v43
	v_exp_f32_e32 v46, v46
	v_exp_f32_e32 v47, v47
	s_waitcnt vmcnt(11)
	v_lshlrev_b32_e32 v44, 16, v96
	v_and_b32_e32 v45, 0xffff0000, v96
	v_pk_fma_f32 v[36:37], v[36:37], v[42:43], v[44:45]
	v_add_f32_e32 v42, 1.0, v46
	v_add_f32_e32 v43, 1.0, v47
	v_rcp_f32_e32 v42, v42
	v_rcp_f32_e32 v43, v43
	v_cvt_pk_bf16_f32 v36, v36, v37
	v_lshlrev_b32_e32 v37, 16, v102
	v_lshlrev_b32_e32 v44, 16, v97
	v_and_b32_e32 v45, 0xffff0000, v97
	v_mul_f32_e32 v37, 0xbfb8aa3b, v37
	v_pk_fma_f32 v[38:39], v[38:39], v[42:43], v[44:45]
	v_exp_f32_e32 v42, v37
	v_and_b32_e32 v37, 0xffff0000, v102
	v_mul_f32_e32 v37, 0xbfb8aa3b, v37
	v_exp_f32_e32 v43, v37
	v_lshlrev_b32_e32 v44, 16, v103
	v_cvt_pk_bf16_f32 v37, v38, v39
	v_add_f32_e32 v38, 1.0, v42
	v_add_f32_e32 v39, 1.0, v43
	v_mul_f32_e32 v44, 0xbfb8aa3b, v44
	v_and_b32_e32 v45, 0xffff0000, v103
	v_rcp_f32_e32 v38, v38
	v_rcp_f32_e32 v39, v39
	v_exp_f32_e32 v44, v44
	v_mul_f32_e32 v45, 0xbfb8aa3b, v45
	v_exp_f32_e32 v45, v45
	v_lshlrev_b32_e32 v42, 16, v98
	v_and_b32_e32 v43, 0xffff0000, v98
	v_pk_fma_f32 v[32:33], v[32:33], v[38:39], v[42:43]
	v_add_f32_e32 v38, 1.0, v44
	v_rcp_f32_e32 v42, v38
	v_add_f32_e32 v38, 1.0, v45
	v_rcp_f32_e32 v43, v38
	v_cvt_pk_bf16_f32 v38, v32, v33
	v_lshlrev_b32_e32 v32, 16, v99
	v_and_b32_e32 v33, 0xffff0000, v99
	v_pk_fma_f32 v[32:33], v[34:35], v[42:43], v[32:33]
	s_waitcnt vmcnt(8)
; __device__ __forceinline__ float bf2f(short s) { return __uint_as_float(((unsigned)(unsigned short)s) << 16); }
; __device__ __forceinline__ float bf2f(u16 u) { return __uint_as_float((unsigned)u << 16); }
; __device__ __forceinline__ unsigned pk2(float lo, float hi) { f32x2_t v = {lo, hi}; bf16x2_t b = __builtin_convertvector(v, bf16x2_t); return __builtin_bit_cast(unsigned, b); }
; __device__ __forceinline__ float sigmoidf_(float x) { return __builtin_amdgcn_rcpf(1.f + __expf(-x)); }
;     __device__ __forceinline__ void operator()(const pg8::f32x4 (&acc)[2][2][4][2], const pg8::Unit& u, int wr, int wc, int fr, int fq) const {
;     ...
;             for (int m = 0; m < 4; ++m) { const size_t row = (size_t)u.pm * 256 + ai * 128 + wr * 64 + m * 16 + fr;
; #pragma unroll
;                 for (int bj = 0; bj < 2; ++bj) { const int col = col0 + bj * 128;
;                     const pg8::f32x4 v0 = acc[ai][bj][m][0], v1 = acc[ai][bj][m][1];
;                     const float r[8] = {v0[0], v0[1], v0[2], v0[3], v1[0], v1[1], v1[2], v1[3]};
;                     const unsigned gws[4] = {gwv[m][bj].x, gwv[m][bj].y, gwv[m][bj].z, gwv[m][bj].w};
;                     const unsigned tws[4] = {twv[m][bj].x, twv[m][bj].y, twv[m][bj].z, twv[m][bj].w};
;                     unsigned ow[4];
; #pragma unroll
;                     for (int e = 0; e < 4; ++e) {
;                         float a0 = sigmoidf_(bf2f((u16)(gws[e] & 0xffffu))) * r[2 * e], a1 = sigmoidf_(bf2f((u16)(gws[e] >> 16))) * r[2 * e + 1];
;                         if (MODE == 1) { a0 += bf2f((u16)(tws[e] & 0xffffu)); a1 += bf2f((u16)(tws[e] >> 16)); }
;                         ow[e] = pk2(a0, a1); }
;                     v4u w = {ow[0], ow[1], ow[2], ow[3]};
;                     *(v4u*)((MODE == 0 ? T1 : MRG) + row * 1024 + col) = w; } }
	v_lshlrev_b32_e32 v34, 16, v88
	v_cvt_pk_bf16_f32 v39, v32, v33
	v_lshlrev_b32_e32 v32, 16, v92
	v_and_b32_e32 v33, 0xffff0000, v92
	v_mul_f32_e32 v32, 0xbfb8aa3b, v32
	v_mul_f32_e32 v33, 0xbfb8aa3b, v33
	v_exp_f32_e32 v32, v32
	v_exp_f32_e32 v33, v33
	global_store_dwordx4 v[40:41], v[36:39], off offset:256
	v_and_b32_e32 v35, 0xffff0000, v88
	v_add_f32_e32 v32, 1.0, v32
	v_lshlrev_b32_e32 v36, 16, v93
	v_and_b32_e32 v37, 0xffff0000, v93
	v_add_f32_e32 v33, 1.0, v33
	v_mul_f32_e32 v36, 0xbfb8aa3b, v36
	v_mul_f32_e32 v37, 0xbfb8aa3b, v37
	v_rcp_f32_e32 v32, v32
	v_rcp_f32_e32 v33, v33
	v_exp_f32_e32 v36, v36
	v_exp_f32_e32 v37, v37
	v_pk_fma_f32 v[28:29], v[28:29], v[32:33], v[34:35]
	v_add_f32_e32 v32, 1.0, v36
	v_add_f32_e32 v33, 1.0, v37
	v_rcp_f32_e32 v32, v32
	v_rcp_f32_e32 v33, v33
	v_cvt_pk_bf16_f32 v28, v28, v29
	v_lshlrev_b32_e32 v29, 16, v94
	v_lshlrev_b32_e32 v34, 16, v89
	v_and_b32_e32 v35, 0xffff0000, v89
	v_mul_f32_e32 v29, 0xbfb8aa3b, v29
	v_pk_fma_f32 v[30:31], v[30:31], v[32:33], v[34:35]
	v_exp_f32_e32 v32, v29
	v_and_b32_e32 v29, 0xffff0000, v94
	v_mul_f32_e32 v29, 0xbfb8aa3b, v29
	v_exp_f32_e32 v33, v29
	v_lshlrev_b32_e32 v34, 16, v95
	v_cvt_pk_bf16_f32 v29, v30, v31
	v_add_f32_e32 v30, 1.0, v32
	v_add_f32_e32 v31, 1.0, v33
	v_mul_f32_e32 v34, 0xbfb8aa3b, v34
	v_and_b32_e32 v35, 0xffff0000, v95
	v_rcp_f32_e32 v30, v30
	v_rcp_f32_e32 v31, v31
	v_exp_f32_e32 v34, v34
	v_mul_f32_e32 v35, 0xbfb8aa3b, v35
	v_exp_f32_e32 v35, v35
	v_lshlrev_b32_e32 v32, 16, v90
	v_and_b32_e32 v33, 0xffff0000, v90
	v_pk_fma_f32 v[24:25], v[24:25], v[30:31], v[32:33]
	v_add_f32_e32 v30, 1.0, v34
	v_rcp_f32_e32 v32, v30
	v_add_f32_e32 v30, 1.0, v35
	v_rcp_f32_e32 v33, v30
	v_cvt_pk_bf16_f32 v30, v24, v25
	v_lshlrev_b32_e32 v24, 16, v91
	v_and_b32_e32 v25, 0xffff0000, v91
	v_pk_fma_f32 v[24:25], v[26:27], v[32:33], v[24:25]
	v_lshlrev_b32_e32 v26, 16, v84
	v_and_b32_e32 v27, 0xffff0000, v84
	v_mul_f32_e32 v26, 0xbfb8aa3b, v26
	v_mul_f32_e32 v27, 0xbfb8aa3b, v27
	v_exp_f32_e32 v26, v26
	v_exp_f32_e32 v27, v27
	v_cvt_pk_bf16_f32 v31, v24, v25
	v_lshl_add_u64 v[24:25], s[10:11], 0, v[114:115]
	v_lshl_add_u64 v[24:25], v[24:25], 0, v[194:195]
	global_store_dwordx4 v[24:25], v[28:31], off
	v_add_f32_e32 v26, 1.0, v26
	v_add_f32_e32 v27, 1.0, v27
	v_lshlrev_b32_e32 v30, 16, v85
	v_and_b32_e32 v31, 0xffff0000, v85
	v_mul_f32_e32 v30, 0xbfb8aa3b, v30
	v_mul_f32_e32 v31, 0xbfb8aa3b, v31
	v_rcp_f32_e32 v26, v26
	v_rcp_f32_e32 v27, v27
	v_exp_f32_e32 v30, v30
	v_exp_f32_e32 v31, v31
	s_waitcnt vmcnt(9)
	v_lshlrev_b32_e32 v28, 16, v80
	v_and_b32_e32 v29, 0xffff0000, v80
	v_pk_fma_f32 v[20:21], v[20:21], v[26:27], v[28:29]
	v_add_f32_e32 v26, 1.0, v30
	v_add_f32_e32 v27, 1.0, v31
	v_rcp_f32_e32 v26, v26
	v_rcp_f32_e32 v27, v27
	v_cvt_pk_bf16_f32 v20, v20, v21
	v_lshlrev_b32_e32 v21, 16, v86
	v_lshlrev_b32_e32 v28, 16, v81
	v_and_b32_e32 v29, 0xffff0000, v81
	v_mul_f32_e32 v21, 0xbfb8aa3b, v21
	v_pk_fma_f32 v[22:23], v[22:23], v[26:27], v[28:29]
	v_exp_f32_e32 v26, v21
	v_and_b32_e32 v21, 0xffff0000, v86
	v_mul_f32_e32 v21, 0xbfb8aa3b, v21
	v_exp_f32_e32 v27, v21
	v_lshlrev_b32_e32 v28, 16, v87
	v_cvt_pk_bf16_f32 v21, v22, v23
	v_add_f32_e32 v22, 1.0, v26
	v_add_f32_e32 v23, 1.0, v27
	v_mul_f32_e32 v28, 0xbfb8aa3b, v28
	v_and_b32_e32 v29, 0xffff0000, v87
	v_rcp_f32_e32 v22, v22
	v_rcp_f32_e32 v23, v23
	v_exp_f32_e32 v28, v28
	v_mul_f32_e32 v29, 0xbfb8aa3b, v29
	v_exp_f32_e32 v29, v29
	v_lshlrev_b32_e32 v26, 16, v82
	v_and_b32_e32 v27, 0xffff0000, v82
	v_pk_fma_f32 v[16:17], v[16:17], v[22:23], v[26:27]
	v_add_f32_e32 v22, 1.0, v28
	v_rcp_f32_e32 v26, v22
	v_add_f32_e32 v22, 1.0, v29
	v_rcp_f32_e32 v27, v22
	v_cvt_pk_bf16_f32 v22, v16, v17
	v_lshlrev_b32_e32 v16, 16, v83
	v_and_b32_e32 v17, 0xffff0000, v83
	v_pk_fma_f32 v[16:17], v[18:19], v[26:27], v[16:17]
	s_waitcnt vmcnt(6)
; __device__ __forceinline__ float bf2f(short s) { return __uint_as_float(((unsigned)(unsigned short)s) << 16); }
; __device__ __forceinline__ float bf2f(u16 u) { return __uint_as_float((unsigned)u << 16); }
; __device__ __forceinline__ unsigned pk2(float lo, float hi) { f32x2_t v = {lo, hi}; bf16x2_t b = __builtin_convertvector(v, bf16x2_t); return __builtin_bit_cast(unsigned, b); }
; __device__ __forceinline__ float sigmoidf_(float x) { return __builtin_amdgcn_rcpf(1.f + __expf(-x)); }
;     __device__ __forceinline__ void operator()(const pg8::f32x4 (&acc)[2][2][4][2], const pg8::Unit& u, int wr, int wc, int fr, int fq) const {
;     ...
;             for (int m = 0; m < 4; ++m) { const size_t row = (size_t)u.pm * 256 + ai * 128 + wr * 64 + m * 16 + fr;
; #pragma unroll
;                 for (int bj = 0; bj < 2; ++bj) { const int col = col0 + bj * 128;
;                     const pg8::f32x4 v0 = acc[ai][bj][m][0], v1 = acc[ai][bj][m][1];
;                     const float r[8] = {v0[0], v0[1], v0[2], v0[3], v1[0], v1[1], v1[2], v1[3]};
;                     const unsigned gws[4] = {gwv[m][bj].x, gwv[m][bj].y, gwv[m][bj].z, gwv[m][bj].w};
;                     const unsigned tws[4] = {twv[m][bj].x, twv[m][bj].y, twv[m][bj].z, twv[m][bj].w};
;                     unsigned ow[4];
; #pragma unroll
;                     for (int e = 0; e < 4; ++e) {
;                         float a0 = sigmoidf_(bf2f((u16)(gws[e] & 0xffffu))) * r[2 * e], a1 = sigmoidf_(bf2f((u16)(gws[e] >> 16))) * r[2 * e + 1];
;                         if (MODE == 1) { a0 += bf2f((u16)(tws[e] & 0xffffu)); a1 += bf2f((u16)(tws[e] >> 16)); }
;                         ow[e] = pk2(a0, a1); }
;                     v4u w = {ow[0], ow[1], ow[2], ow[3]};
;                     *(v4u*)((MODE == 0 ? T1 : MRG) + row * 1024 + col) = w; } }
	v_lshlrev_b32_e32 v18, 16, v72
	v_cvt_pk_bf16_f32 v23, v16, v17
	v_lshlrev_b32_e32 v16, 16, v76
	v_and_b32_e32 v17, 0xffff0000, v76
	v_mul_f32_e32 v16, 0xbfb8aa3b, v16
	v_mul_f32_e32 v17, 0xbfb8aa3b, v17
	v_exp_f32_e32 v16, v16
	v_exp_f32_e32 v17, v17
	global_store_dwordx4 v[24:25], v[20:23], off offset:256
	v_and_b32_e32 v19, 0xffff0000, v72
	v_add_f32_e32 v16, 1.0, v16
	v_lshlrev_b32_e32 v20, 16, v77
	v_and_b32_e32 v21, 0xffff0000, v77
	v_add_f32_e32 v17, 1.0, v17
	v_mul_f32_e32 v20, 0xbfb8aa3b, v20
	v_mul_f32_e32 v21, 0xbfb8aa3b, v21
	v_rcp_f32_e32 v16, v16
	v_rcp_f32_e32 v17, v17
	v_exp_f32_e32 v20, v20
	v_exp_f32_e32 v21, v21
	v_pk_fma_f32 v[12:13], v[12:13], v[16:17], v[18:19]
	v_add_f32_e32 v16, 1.0, v20
	v_add_f32_e32 v17, 1.0, v21
	v_rcp_f32_e32 v16, v16
	v_rcp_f32_e32 v17, v17
	v_cvt_pk_bf16_f32 v12, v12, v13
	v_lshlrev_b32_e32 v13, 16, v78
	v_lshlrev_b32_e32 v18, 16, v73
	v_and_b32_e32 v19, 0xffff0000, v73
	v_mul_f32_e32 v13, 0xbfb8aa3b, v13
	v_pk_fma_f32 v[14:15], v[14:15], v[16:17], v[18:19]
	v_exp_f32_e32 v16, v13
	v_and_b32_e32 v13, 0xffff0000, v78
	v_mul_f32_e32 v13, 0xbfb8aa3b, v13
	v_exp_f32_e32 v17, v13
	v_lshlrev_b32_e32 v18, 16, v79
	v_cvt_pk_bf16_f32 v13, v14, v15
	v_add_f32_e32 v14, 1.0, v16
	v_add_f32_e32 v15, 1.0, v17
	v_mul_f32_e32 v18, 0xbfb8aa3b, v18
	v_and_b32_e32 v19, 0xffff0000, v79
	v_rcp_f32_e32 v14, v14
	v_rcp_f32_e32 v15, v15
	v_exp_f32_e32 v18, v18
	v_mul_f32_e32 v19, 0xbfb8aa3b, v19
	v_exp_f32_e32 v19, v19
	v_lshlrev_b32_e32 v16, 16, v74
	v_and_b32_e32 v17, 0xffff0000, v74
	v_pk_fma_f32 v[8:9], v[8:9], v[14:15], v[16:17]
	v_add_f32_e32 v14, 1.0, v18
	v_rcp_f32_e32 v16, v14
	v_add_f32_e32 v14, 1.0, v19
	v_rcp_f32_e32 v17, v14
	v_cvt_pk_bf16_f32 v14, v8, v9
	v_lshlrev_b32_e32 v8, 16, v75
	v_and_b32_e32 v9, 0xffff0000, v75
	v_pk_fma_f32 v[8:9], v[10:11], v[16:17], v[8:9]
	v_lshlrev_b32_e32 v10, 16, v68
	v_and_b32_e32 v11, 0xffff0000, v68
	v_mul_f32_e32 v10, 0xbfb8aa3b, v10
	v_mul_f32_e32 v11, 0xbfb8aa3b, v11
	v_exp_f32_e32 v10, v10
	v_exp_f32_e32 v11, v11
	v_cvt_pk_bf16_f32 v15, v8, v9
	v_lshl_add_u64 v[8:9], s[10:11], 0, v[112:113]
	v_lshl_add_u64 v[8:9], v[8:9], 0, v[194:195]
	global_store_dwordx4 v[8:9], v[12:15], off
	v_add_f32_e32 v10, 1.0, v10
	v_add_f32_e32 v11, 1.0, v11
	v_lshlrev_b32_e32 v14, 16, v69
	v_and_b32_e32 v15, 0xffff0000, v69
	v_mul_f32_e32 v14, 0xbfb8aa3b, v14
	v_mul_f32_e32 v15, 0xbfb8aa3b, v15
	v_rcp_f32_e32 v10, v10
	v_rcp_f32_e32 v11, v11
	v_exp_f32_e32 v14, v14
	v_exp_f32_e32 v15, v15
	s_waitcnt vmcnt(7)
	v_lshlrev_b32_e32 v12, 16, v64
	v_and_b32_e32 v13, 0xffff0000, v64
	v_pk_fma_f32 v[4:5], v[4:5], v[10:11], v[12:13]
	v_add_f32_e32 v10, 1.0, v14
	v_add_f32_e32 v11, 1.0, v15
	v_rcp_f32_e32 v10, v10
	v_rcp_f32_e32 v11, v11
	v_cvt_pk_bf16_f32 v4, v4, v5
	v_lshlrev_b32_e32 v5, 16, v70
	v_lshlrev_b32_e32 v12, 16, v65
	v_and_b32_e32 v13, 0xffff0000, v65
	v_mul_f32_e32 v5, 0xbfb8aa3b, v5
	v_pk_fma_f32 v[6:7], v[6:7], v[10:11], v[12:13]
	v_exp_f32_e32 v10, v5
	v_and_b32_e32 v5, 0xffff0000, v70
	v_mul_f32_e32 v5, 0xbfb8aa3b, v5
	v_exp_f32_e32 v11, v5
	v_lshlrev_b32_e32 v12, 16, v71
	v_cvt_pk_bf16_f32 v5, v6, v7
	v_add_f32_e32 v6, 1.0, v10
	v_add_f32_e32 v7, 1.0, v11
	v_mul_f32_e32 v12, 0xbfb8aa3b, v12
	v_and_b32_e32 v13, 0xffff0000, v71
	v_rcp_f32_e32 v6, v6
	v_rcp_f32_e32 v7, v7
	v_exp_f32_e32 v12, v12
	v_mul_f32_e32 v13, 0xbfb8aa3b, v13
	v_exp_f32_e32 v13, v13
	v_lshlrev_b32_e32 v10, 16, v66
	v_and_b32_e32 v11, 0xffff0000, v66
	v_pk_fma_f32 v[0:1], v[0:1], v[6:7], v[10:11]
	v_add_f32_e32 v6, 1.0, v12
	v_rcp_f32_e32 v10, v6
	v_add_f32_e32 v6, 1.0, v13
	v_rcp_f32_e32 v11, v6
	v_cvt_pk_bf16_f32 v6, v0, v1
	v_lshlrev_b32_e32 v0, 16, v67
	v_and_b32_e32 v1, 0xffff0000, v67
	v_pk_fma_f32 v[0:1], v[2:3], v[10:11], v[0:1]
	s_nop 0
	v_cvt_pk_bf16_f32 v7, v0, v1
	global_store_dwordx4 v[8:9], v[4:7], off offset:256
	s_cbranch_vccnz .LBB0_641
	s_andn2_b64 vcc, exec, s[4:5]
	s_cbranch_vccnz .LBB0_640
	s_barrier
	s_branch .LBB0_640

; #define LAS __attribute__((address_space(3)))
; __global__ void __launch_bounds__(512) mk_fwd(Args a) {
;     extern __shared__ __attribute__((aligned(16))) unsigned char lds[];
;     cg::grid_group grid = cg::this_grid();
;     unsigned char* ws = a.ws;
;     LAS unsigned char* lds3 = (LAS unsigned char*)lds;
;     const int G = gridDim.x, bx = blockIdx.x;
;     const int mk_wid = __builtin_amdgcn_readfirstlane(threadIdx.x >> 6);
	.amdhsa_kernel _Z6mk_fwd4Args
		.amdhsa_group_segment_fixed_size 0
		.amdhsa_private_segment_fixed_size 0
		.amdhsa_kernarg_size 448
		.amdhsa_user_sgpr_count 2
		.amdhsa_user_sgpr_dispatch_ptr 0
		.amdhsa_user_sgpr_queue_ptr 0
		.amdhsa_user_sgpr_kernarg_segment_ptr 1
		.amdhsa_user_sgpr_dispatch_id 0
		.amdhsa_user_sgpr_kernarg_preload_length 0
		.amdhsa_user_sgpr_kernarg_preload_offset 0
		.amdhsa_user_sgpr_private_segment_size 0
		.amdhsa_uses_dynamic_stack 0
		.amdhsa_enable_private_segment 0
		.amdhsa_system_sgpr_workgroup_id_x 1
		.amdhsa_system_sgpr_workgroup_id_y 0
		.amdhsa_system_sgpr_workgroup_id_z 0
		.amdhsa_system_sgpr_workgroup_info 0
		.amdhsa_system_vgpr_workitem_id 2
		.amdhsa_next_free_vgpr 256
		.amdhsa_next_free_sgpr 100
		.amdhsa_accum_offset 256
		.amdhsa_reserve_vcc 1
		.amdhsa_float_round_mode_32 0
		.amdhsa_float_round_mode_16_64 0
		.amdhsa_float_denorm_mode_32 3
		.amdhsa_float_denorm_mode_16_64 3
		.amdhsa_dx10_clamp 1
		.amdhsa_ieee_mode 1
		.amdhsa_fp16_overflow 0
		.amdhsa_tg_split 0
		.amdhsa_exception_fp_ieee_invalid_op 0
		.amdhsa_exception_fp_denorm_src 0
		.amdhsa_exception_fp_ieee_div_zero 0
		.amdhsa_exception_fp_ieee_overflow 0
		.amdhsa_exception_fp_ieee_underflow 0
		.amdhsa_exception_fp_ieee_inexact 0
		.amdhsa_exception_int_div_zero 0
	.end_amdhsa_kernel

; #define LAS __attribute__((address_space(3)))
; __global__ void __launch_bounds__(512) mk_fwd(Args a) {
;     extern __shared__ __attribute__((aligned(16))) unsigned char lds[];
;     cg::grid_group grid = cg::this_grid();
;     unsigned char* ws = a.ws;
;     LAS unsigned char* lds3 = (LAS unsigned char*)lds;
;     const int G = gridDim.x, bx = blockIdx.x;
;     const int mk_wid = __builtin_amdgcn_readfirstlane(threadIdx.x >> 6);
amdhsa.kernels:
  - .agpr_count:     0
    .args:
      - .offset:         0
        .size:           192
        .value_kind:     by_value
      - .offset:         192
        .size:           4
        .value_kind:     hidden_block_count_x
      - .offset:         196
        .size:           4
        .value_kind:     hidden_block_count_y
      - .offset:         200
        .size:           4
        .value_kind:     hidden_block_count_z
      - .offset:         204
        .size:           2
        .value_kind:     hidden_group_size_x
      - .offset:         206
        .size:           2
        .value_kind:     hidden_group_size_y
      - .offset:         208
        .size:           2
        .value_kind:     hidden_group_size_z
      - .offset:         210
        .size:           2
        .value_kind:     hidden_remainder_x
      - .offset:         212
        .size:           2
        .value_kind:     hidden_remainder_y
      - .offset:         214
        .size:           2
        .value_kind:     hidden_remainder_z
      - .offset:         232
        .size:           8
        .value_kind:     hidden_global_offset_x
      - .offset:         240
        .size:           8
        .value_kind:     hidden_global_offset_y
      - .offset:         248
        .size:           8
        .value_kind:     hidden_global_offset_z
      - .offset:         256
        .size:           2
        .value_kind:     hidden_grid_dims
      - .offset:         280
        .size:           8
        .value_kind:     hidden_multigrid_sync_arg
      - .offset:         312
        .size:           4
        .value_kind:     hidden_dynamic_lds_size
    .group_segment_fixed_size: 0
    .kernarg_segment_align: 8
    .kernarg_segment_size: 448
    .language:       OpenCL C
    .language_version:
      - 2
      - 0
    .max_flat_workgroup_size: 512
    .name:           _Z6mk_fwd4Args
    .private_segment_fixed_size: 0
    .sgpr_count:     106
    .sgpr_spill_count: 0
    .symbol:         _Z6mk_fwd4Args.kd
    .uniform_work_group_size: 1
    .uses_dynamic_stack: false
    .vgpr_count:     256
    .vgpr_spill_count: 0
    .wavefront_size: 64
